# move last 3 of 6 SP2 LDS-DMA loads into the following MFMA block in all four GEMM K-loops (vmcnt 8->5)
# speedup vs baseline: 1.0203x; 1.0031x over previous
; #define PG8_STAGE(bufoff, gbase, voff) do { _Pragma("unroll") for (int _i = 0; _i < 2; ++_i) \
;         __builtin_amdgcn_global_load_lds((const unsigned*)((const char*)(gbase) + (voff)[_i]), (PG8_LAS unsigned*)(lds + (bufoff) + ldsw + _i * 8192), 16, 0, 0); } while (0)
; #define PG8_LDA(dst, b, h) do { _Pragma("unroll") for (int m = 0; m < 4; ++m) _Pragma("unroll") for (int k = 0; k < 2; ++k) dst[m][k] = *(const PG8_LAS bf16x8*)(lds + PG8_SA(b, h) + aoff + m * 2048 + k * 1024); } while (0)
; #define PG8_LDB(dst, b, h) do { _Pragma("unroll") for (int n = 0; n < 2; ++n) _Pragma("unroll") for (int k = 0; k < 2; ++k) dst[n][k] = *(const PG8_LAS bf16x8*)(lds + PG8_SB(b, h) + boff + n * 2048 + k * 1024); } while (0)
; #define PG8_MMA(ai, bj, At, Bt) do { __builtin_amdgcn_s_setprio(1); _Pragma("unroll") for (int m = 0; m < 4; ++m) _Pragma("unroll") for (int n = 0; n < 2; ++n) _Pragma("unroll") for (int k = 0; k < 2; ++k) \
;         acc[ai][bj][m][n] = __builtin_amdgcn_mfma_f32_16x16x32_bf16(Bt[n][k], At[m][k], acc[ai][bj][m][n], 0, 0, 0); __builtin_amdgcn_s_setprio(0); } while (0)
; #define PG8_WAIT_V(n) asm volatile("s_waitcnt vmcnt(" #n ")" ::: "memory")
; #define PG8_WAIT_L(n) asm volatile("s_waitcnt lgkmcnt(" #n ")" ::: "memory")
; #define PG8_BAR __builtin_amdgcn_s_barrier()
; #define PG8_SCHED __builtin_amdgcn_sched_barrier(0)
; template <class Epi, class Sched, bool ALIGN_EPI = false, bool SP2 = false>
; __device__ __forceinline__ void gemm_phase(PG8_LAS unsigned char* lds, const Gemm g, const Sched& S, const Epi& E) {
;     ...
;             PG8_LDB(B0, 0, 0); PG8_LDB(B1, 0, 1); PG8_SCHED; PG8_LDA(At, 0, 0); PG8_STAGE(PG8_SA(1, 1), a1 + hstep, voffA);
;             PG8_WAIT_V(8); PG8_WAIT_L(0); PG8_BAR; PG8_MMA(0, 0, At, B0); PG8_MMA(0, 1, At, B1); PG8_BAR; PG8_SCHED;
;             PG8_LDA(At, 0, 1); PG8_STAGE(PG8_SB(0, 0), b2, voffB); PG8_STAGE(PG8_SB(0, 1), b2 + hstep, voffB); PG8_STAGE(PG8_SA(0, 0), a2, voffA);
.LBB0_387:
	ds_read_b128 v[128:131], v171
	ds_read_b128 v[132:135], v171 offset:1024
	ds_read_b128 v[136:139], v171 offset:2048
	ds_read_b128 v[182:185], v171 offset:3072
	ds_read_b128 v[186:189], v173
	ds_read_b128 v[190:193], v173 offset:1024
	ds_read_b128 v[194:197], v173 offset:2048
	ds_read_b128 v[198:201], v173 offset:3072
	s_add_u32 s77, s82, 0xfffc0080
	s_addc_u32 s84, s83, -1
	s_cmp_eq_u32 s75, 12
	s_cselect_b32 s87, s2, s84
	s_cselect_b32 s86, s7, s77
	s_cselect_b32 s85, s12, s45
	s_cselect_b32 s84, s17, s44
	v_lshl_add_u64 v[168:169], s[82:83], 0, v[158:159]
	s_add_i32 m0, s11, 0xc000
	ds_read_b128 v[202:205], v175
	ds_read_b128 v[206:209], v175 offset:1024
	ds_read_b128 v[210:213], v175 offset:2048
	ds_read_b128 v[214:217], v175 offset:3072
	ds_read_b128 v[218:221], v175 offset:4096
	ds_read_b128 v[226:229], v175 offset:5120
	ds_read_b128 v[230:233], v175 offset:6144
	ds_read_b128 v[236:239], v175 offset:7168
	global_load_lds_dwordx4 v[168:169], off
	v_lshl_add_u64 v[168:169], s[82:83], 0, v[160:161]
	s_add_i32 m0, s11, 0xe000
	s_nop 0
	global_load_lds_dwordx4 v[168:169], off
	s_waitcnt vmcnt(8)
	s_waitcnt lgkmcnt(0)
	s_barrier
	s_setprio 1
	s_waitcnt lgkmcnt(0)
	v_mfma_f32_16x16x32_bf16 v[124:127], v[128:131], v[202:205], v[124:127]
	v_mfma_f32_16x16x32_bf16 v[116:119], v[136:139], v[202:205], v[116:119]
	v_mfma_f32_16x16x32_bf16 v[108:111], v[128:131], v[210:213], v[108:111]
	v_mfma_f32_16x16x32_bf16 v[100:103], v[136:139], v[210:213], v[100:103]
	v_mfma_f32_16x16x32_bf16 v[92:95], v[128:131], v[218:221], v[92:95]
	v_mfma_f32_16x16x32_bf16 v[84:87], v[136:139], v[218:221], v[84:87]
	v_mfma_f32_16x16x32_bf16 v[76:79], v[128:131], v[230:233], v[76:79]
	v_mfma_f32_16x16x32_bf16 v[68:71], v[136:139], v[230:233], v[68:71]
	v_mfma_f32_16x16x32_bf16 v[124:127], v[132:135], v[206:209], v[124:127]
	v_mfma_f32_16x16x32_bf16 v[116:119], v[182:185], v[206:209], v[116:119]
	v_mfma_f32_16x16x32_bf16 v[108:111], v[132:135], v[214:217], v[108:111]
	v_mfma_f32_16x16x32_bf16 v[100:103], v[182:185], v[214:217], v[100:103]
	v_mfma_f32_16x16x32_bf16 v[92:95], v[132:135], v[226:229], v[92:95]
	v_mfma_f32_16x16x32_bf16 v[84:87], v[182:185], v[226:229], v[84:87]
	v_mfma_f32_16x16x32_bf16 v[76:79], v[132:135], v[236:239], v[76:79]
	v_mfma_f32_16x16x32_bf16 v[68:71], v[182:185], v[236:239], v[68:71]
	s_setprio 0
	s_setprio 1
	v_mfma_f32_16x16x32_bf16 v[120:123], v[186:189], v[202:205], v[120:123]
	v_mfma_f32_16x16x32_bf16 v[112:115], v[194:197], v[202:205], v[112:115]
	v_mfma_f32_16x16x32_bf16 v[104:107], v[186:189], v[210:213], v[104:107]
	v_mfma_f32_16x16x32_bf16 v[96:99], v[194:197], v[210:213], v[96:99]
	v_mfma_f32_16x16x32_bf16 v[88:91], v[186:189], v[218:221], v[88:91]
	v_mfma_f32_16x16x32_bf16 v[80:83], v[194:197], v[218:221], v[80:83]
	v_mfma_f32_16x16x32_bf16 v[72:75], v[186:189], v[230:233], v[72:75]
	v_mfma_f32_16x16x32_bf16 v[64:67], v[194:197], v[230:233], v[64:67]
	v_mfma_f32_16x16x32_bf16 v[120:123], v[190:193], v[206:209], v[120:123]
	v_mfma_f32_16x16x32_bf16 v[112:115], v[198:201], v[206:209], v[112:115]
	v_mfma_f32_16x16x32_bf16 v[104:107], v[190:193], v[214:217], v[104:107]
	v_mfma_f32_16x16x32_bf16 v[96:99], v[198:201], v[214:217], v[96:99]
	v_mfma_f32_16x16x32_bf16 v[88:91], v[190:193], v[226:229], v[88:91]
	v_mfma_f32_16x16x32_bf16 v[80:83], v[198:201], v[226:229], v[80:83]
	v_mfma_f32_16x16x32_bf16 v[72:75], v[190:193], v[236:239], v[72:75]
	v_mfma_f32_16x16x32_bf16 v[64:67], v[198:201], v[236:239], v[64:67]
	s_setprio 0
	s_barrier
	s_add_i32 s77, s31, s71
	v_lshl_add_u64 v[168:169], s[84:85], 0, v[142:143]
	s_mov_b32 m0, s77
	ds_read_b128 v[202:205], v175 offset:16384
	ds_read_b128 v[206:209], v175 offset:17408
	ds_read_b128 v[210:213], v175 offset:18432
	ds_read_b128 v[214:217], v175 offset:19456
	ds_read_b128 v[218:221], v175 offset:20480
	ds_read_b128 v[226:229], v175 offset:21504
	ds_read_b128 v[230:233], v175 offset:22528
	ds_read_b128 v[236:239], v175 offset:23552
	global_load_lds_dwordx4 v[168:169], off
	s_add_i32 m0, s77, 0x2000
	s_add_u32 s90, s84, 0x40000
	v_lshl_add_u64 v[178:179], s[84:85], 0, v[146:147]
	s_addc_u32 s91, s85, 0
	s_add_i32 s77, s22, s71
	global_load_lds_dwordx4 v[178:179], off
	v_lshl_add_u64 v[222:223], s[90:91], 0, v[142:143]
	s_mov_b32 m0, s77
	v_lshl_add_u64 v[240:241], s[86:87], 0, v[144:145]
	global_load_lds_dwordx4 v[222:223], off
	v_lshl_add_u64 v[244:245], s[90:91], 0, v[146:147]
	v_lshl_add_u64 v[222:223], s[86:87], 0, v[140:141]
	s_waitcnt vmcnt(5)
	s_waitcnt lgkmcnt(0)
	s_barrier
; #define PG8_STAGE(bufoff, gbase, voff) do { _Pragma("unroll") for (int _i = 0; _i < 2; ++_i) \
;         __builtin_amdgcn_global_load_lds((const unsigned*)((const char*)(gbase) + (voff)[_i]), (PG8_LAS unsigned*)(lds + (bufoff) + ldsw + _i * 8192), 16, 0, 0); } while (0)
; #define PG8_LDA(dst, b, h) do { _Pragma("unroll") for (int m = 0; m < 4; ++m) _Pragma("unroll") for (int k = 0; k < 2; ++k) dst[m][k] = *(const PG8_LAS bf16x8*)(lds + PG8_SA(b, h) + aoff + m * 2048 + k * 1024); } while (0)
; #define PG8_LDB(dst, b, h) do { _Pragma("unroll") for (int n = 0; n < 2; ++n) _Pragma("unroll") for (int k = 0; k < 2; ++k) dst[n][k] = *(const PG8_LAS bf16x8*)(lds + PG8_SB(b, h) + boff + n * 2048 + k * 1024); } while (0)
; #define PG8_MMA(ai, bj, At, Bt) do { __builtin_amdgcn_s_setprio(1); _Pragma("unroll") for (int m = 0; m < 4; ++m) _Pragma("unroll") for (int n = 0; n < 2; ++n) _Pragma("unroll") for (int k = 0; k < 2; ++k) \
;         acc[ai][bj][m][n] = __builtin_amdgcn_mfma_f32_16x16x32_bf16(Bt[n][k], At[m][k], acc[ai][bj][m][n], 0, 0, 0); __builtin_amdgcn_s_setprio(0); } while (0)
; #define PG8_WAIT_V(n) asm volatile("s_waitcnt vmcnt(" #n ")" ::: "memory")
; #define PG8_WAIT_L(n) asm volatile("s_waitcnt lgkmcnt(" #n ")" ::: "memory")
; #define PG8_BAR __builtin_amdgcn_s_barrier()
; #define PG8_SCHED __builtin_amdgcn_sched_barrier(0)
; template <class Epi, class Sched, bool ALIGN_EPI = false, bool SP2 = false>
; __device__ __forceinline__ void gemm_phase(PG8_LAS unsigned char* lds, const Gemm g, const Sched& S, const Epi& E) {
;     ...
;             PG8_WAIT_V(8); PG8_WAIT_L(0); PG8_BAR; PG8_MMA(1, 0, At, B0); PG8_MMA(1, 1, At, B1); PG8_BAR; PG8_SCHED;
;             PG8_LDB(B0, 1, 0); PG8_LDB(B1, 1, 1); PG8_SCHED; PG8_LDA(At, 1, 0); PG8_STAGE(PG8_SA(0, 1), a2 + hstep, voffA);
;             PG8_WAIT_V(8); PG8_WAIT_L(0); PG8_BAR; PG8_MMA(0, 0, At, B0); PG8_MMA(0, 1, At, B1); PG8_BAR; PG8_SCHED;
	s_setprio 1
	s_waitcnt lgkmcnt(0)
	v_mfma_f32_16x16x32_bf16 v[60:63], v[128:131], v[202:205], v[60:63]
	v_mfma_f32_16x16x32_bf16 v[52:55], v[136:139], v[202:205], v[52:55]
	v_mfma_f32_16x16x32_bf16 v[44:47], v[128:131], v[210:213], v[44:47]
	v_mfma_f32_16x16x32_bf16 v[36:39], v[136:139], v[210:213], v[36:39]
	s_add_i32 m0, s77, 0x2000
	v_mfma_f32_16x16x32_bf16 v[28:31], v[128:131], v[218:221], v[28:31]
	global_load_lds_dwordx4 v[244:245], off
	v_mfma_f32_16x16x32_bf16 v[20:23], v[136:139], v[218:221], v[20:23]
	v_mfma_f32_16x16x32_bf16 v[12:15], v[128:131], v[230:233], v[12:15]
	v_mfma_f32_16x16x32_bf16 v[4:7], v[136:139], v[230:233], v[4:7]
	v_mfma_f32_16x16x32_bf16 v[60:63], v[132:135], v[206:209], v[60:63]
	v_mfma_f32_16x16x32_bf16 v[52:55], v[182:185], v[206:209], v[52:55]
	v_mfma_f32_16x16x32_bf16 v[44:47], v[132:135], v[214:217], v[44:47]
	v_mfma_f32_16x16x32_bf16 v[36:39], v[182:185], v[214:217], v[36:39]
	s_mov_b32 m0, s11
	v_mfma_f32_16x16x32_bf16 v[28:31], v[132:135], v[226:229], v[28:31]
	global_load_lds_dwordx4 v[222:223], off
	v_mfma_f32_16x16x32_bf16 v[20:23], v[182:185], v[226:229], v[20:23]
	v_mfma_f32_16x16x32_bf16 v[12:15], v[132:135], v[236:239], v[12:15]
	v_mfma_f32_16x16x32_bf16 v[4:7], v[182:185], v[236:239], v[4:7]
	s_setprio 0
	s_setprio 1
	v_mfma_f32_16x16x32_bf16 v[56:59], v[186:189], v[202:205], v[56:59]
	v_mfma_f32_16x16x32_bf16 v[48:51], v[194:197], v[202:205], v[48:51]
	v_mfma_f32_16x16x32_bf16 v[40:43], v[186:189], v[210:213], v[40:43]
	v_mfma_f32_16x16x32_bf16 v[32:35], v[194:197], v[210:213], v[32:35]
	s_mov_b32 m0, s89
	v_mfma_f32_16x16x32_bf16 v[24:27], v[186:189], v[218:221], v[24:27]
	global_load_lds_dwordx4 v[240:241], off
	v_mfma_f32_16x16x32_bf16 v[16:19], v[194:197], v[218:221], v[16:19]
	v_mfma_f32_16x16x32_bf16 v[8:11], v[186:189], v[230:233], v[8:11]
	v_mfma_f32_16x16x32_bf16 v[0:3], v[194:197], v[230:233], v[0:3]
	v_mfma_f32_16x16x32_bf16 v[56:59], v[190:193], v[206:209], v[56:59]
	v_mfma_f32_16x16x32_bf16 v[48:51], v[198:201], v[206:209], v[48:51]
	v_mfma_f32_16x16x32_bf16 v[40:43], v[190:193], v[214:217], v[40:43]
	v_mfma_f32_16x16x32_bf16 v[32:35], v[198:201], v[214:217], v[32:35]
	v_mfma_f32_16x16x32_bf16 v[24:27], v[190:193], v[226:229], v[24:27]
	v_mfma_f32_16x16x32_bf16 v[16:19], v[198:201], v[226:229], v[16:19]
	v_mfma_f32_16x16x32_bf16 v[8:11], v[190:193], v[236:239], v[8:11]
	v_mfma_f32_16x16x32_bf16 v[0:3], v[198:201], v[236:239], v[0:3]
	s_setprio 0
	s_barrier
	s_add_i32 s77, 0, 0x18000
	v_add_u32_e32 v148, s77, v167
	s_add_i32 s88, 0, 0x1c000
	ds_read_b128 v[128:131], v148
	ds_read_b128 v[132:135], v148 offset:1024
	ds_read_b128 v[136:139], v148 offset:2048
	ds_read_b128 v[182:185], v148 offset:3072
	v_add_u32_e32 v148, s88, v167
	ds_read_b128 v[186:189], v148
	ds_read_b128 v[190:193], v148 offset:1024
	ds_read_b128 v[194:197], v148 offset:2048
	ds_read_b128 v[198:201], v148 offset:3072
	s_add_u32 s86, s86, 0x40000
	s_addc_u32 s87, s87, 0
	s_mov_b32 m0, s95
	v_lshl_add_u64 v[242:243], s[86:87], 0, v[140:141]
	ds_read_b128 v[202:205], v175 offset:32768
	ds_read_b128 v[206:209], v175 offset:33792
	ds_read_b128 v[210:213], v175 offset:34816
	ds_read_b128 v[214:217], v175 offset:35840
	ds_read_b128 v[218:221], v175 offset:36864
	ds_read_b128 v[226:229], v175 offset:37888
	ds_read_b128 v[230:233], v175 offset:38912
	ds_read_b128 v[236:239], v175 offset:39936
	global_load_lds_dwordx4 v[242:243], off
	v_lshl_add_u64 v[242:243], s[86:87], 0, v[144:145]
	s_mov_b32 m0, s96
	s_nop 0
	global_load_lds_dwordx4 v[242:243], off
	s_waitcnt vmcnt(8)
	s_waitcnt lgkmcnt(0)
	s_barrier
	s_setprio 1
	s_waitcnt lgkmcnt(0)
	v_mfma_f32_16x16x32_bf16 v[124:127], v[128:131], v[202:205], v[124:127]
	v_mfma_f32_16x16x32_bf16 v[116:119], v[136:139], v[202:205], v[116:119]
	v_mfma_f32_16x16x32_bf16 v[108:111], v[128:131], v[210:213], v[108:111]
	v_mfma_f32_16x16x32_bf16 v[100:103], v[136:139], v[210:213], v[100:103]
	v_mfma_f32_16x16x32_bf16 v[92:95], v[128:131], v[218:221], v[92:95]
	v_mfma_f32_16x16x32_bf16 v[84:87], v[136:139], v[218:221], v[84:87]
	v_mfma_f32_16x16x32_bf16 v[76:79], v[128:131], v[230:233], v[76:79]
	v_mfma_f32_16x16x32_bf16 v[68:71], v[136:139], v[230:233], v[68:71]
	v_mfma_f32_16x16x32_bf16 v[124:127], v[132:135], v[206:209], v[124:127]
	v_mfma_f32_16x16x32_bf16 v[116:119], v[182:185], v[206:209], v[116:119]
	v_mfma_f32_16x16x32_bf16 v[108:111], v[132:135], v[214:217], v[108:111]
	v_mfma_f32_16x16x32_bf16 v[100:103], v[182:185], v[214:217], v[100:103]
	v_mfma_f32_16x16x32_bf16 v[92:95], v[132:135], v[226:229], v[92:95]
	v_mfma_f32_16x16x32_bf16 v[84:87], v[182:185], v[226:229], v[84:87]
	v_mfma_f32_16x16x32_bf16 v[76:79], v[132:135], v[236:239], v[76:79]
	v_mfma_f32_16x16x32_bf16 v[68:71], v[182:185], v[236:239], v[68:71]
	s_setprio 0
	s_setprio 1
	v_mfma_f32_16x16x32_bf16 v[120:123], v[186:189], v[202:205], v[120:123]
	v_mfma_f32_16x16x32_bf16 v[112:115], v[194:197], v[202:205], v[112:115]
	v_mfma_f32_16x16x32_bf16 v[104:107], v[186:189], v[210:213], v[104:107]
	v_mfma_f32_16x16x32_bf16 v[96:99], v[194:197], v[210:213], v[96:99]
	v_mfma_f32_16x16x32_bf16 v[88:91], v[186:189], v[218:221], v[88:91]
	v_mfma_f32_16x16x32_bf16 v[80:83], v[194:197], v[218:221], v[80:83]
	v_mfma_f32_16x16x32_bf16 v[72:75], v[186:189], v[230:233], v[72:75]
	v_mfma_f32_16x16x32_bf16 v[64:67], v[194:197], v[230:233], v[64:67]
	v_mfma_f32_16x16x32_bf16 v[120:123], v[190:193], v[206:209], v[120:123]
	v_mfma_f32_16x16x32_bf16 v[112:115], v[198:201], v[206:209], v[112:115]
	v_mfma_f32_16x16x32_bf16 v[104:107], v[190:193], v[214:217], v[104:107]
	v_mfma_f32_16x16x32_bf16 v[96:99], v[198:201], v[214:217], v[96:99]
	v_mfma_f32_16x16x32_bf16 v[88:91], v[190:193], v[226:229], v[88:91]
	v_mfma_f32_16x16x32_bf16 v[80:83], v[198:201], v[226:229], v[80:83]
	v_mfma_f32_16x16x32_bf16 v[72:75], v[190:193], v[236:239], v[72:75]
	v_mfma_f32_16x16x32_bf16 v[64:67], v[198:201], v[236:239], v[64:67]
	s_setprio 0
	s_barrier
; #define PG8_STAGE(bufoff, gbase, voff) do { _Pragma("unroll") for (int _i = 0; _i < 2; ++_i) \
;         __builtin_amdgcn_global_load_lds((const unsigned*)((const char*)(gbase) + (voff)[_i]), (PG8_LAS unsigned*)(lds + (bufoff) + ldsw + _i * 8192), 16, 0, 0); } while (0)
; #define PG8_LDA(dst, b, h) do { _Pragma("unroll") for (int m = 0; m < 4; ++m) _Pragma("unroll") for (int k = 0; k < 2; ++k) dst[m][k] = *(const PG8_LAS bf16x8*)(lds + PG8_SA(b, h) + aoff + m * 2048 + k * 1024); } while (0)
; #define PG8_MMA(ai, bj, At, Bt) do { __builtin_amdgcn_s_setprio(1); _Pragma("unroll") for (int m = 0; m < 4; ++m) _Pragma("unroll") for (int n = 0; n < 2; ++n) _Pragma("unroll") for (int k = 0; k < 2; ++k) \
;         acc[ai][bj][m][n] = __builtin_amdgcn_mfma_f32_16x16x32_bf16(Bt[n][k], At[m][k], acc[ai][bj][m][n], 0, 0, 0); __builtin_amdgcn_s_setprio(0); } while (0)
; #define PG8_WAIT_V(n) asm volatile("s_waitcnt vmcnt(" #n ")" ::: "memory")
; #define PG8_WAIT_L(n) asm volatile("s_waitcnt lgkmcnt(" #n ")" ::: "memory")
; #define PG8_BAR __builtin_amdgcn_s_barrier()
; #define PG8_SCHED __builtin_amdgcn_sched_barrier(0)
; template <class Epi, class Sched, bool ALIGN_EPI = false, bool SP2 = false>
; __device__ __forceinline__ void gemm_phase(PG8_LAS unsigned char* lds, const Gemm g, const Sched& S, const Epi& E) {
;     ...
;         for (int t = 0; t < nt; t += 2) {
;             const bool last = (t == nt - 2);
;             const char* a1 = cA + (size_t)(t + 1) * kstep;
;             const char* a2 = last ? nA : cA + (size_t)(t + 2) * kstep; const char* b2 = last ? nB : cB + (size_t)(t + 2) * kstep;
;             const char* a3 = a2 + kstep; const char* b3 = b2 + kstep;
;     ...
;             PG8_LDA(At, 1, 1); PG8_STAGE(PG8_SB(1, 0), b3, voffB); PG8_STAGE(PG8_SB(1, 1), b3 + hstep, voffB); PG8_STAGE(PG8_SA(1, 0), a3, voffA);
;             PG8_WAIT_V(8); PG8_WAIT_L(0); PG8_BAR; PG8_MMA(1, 0, At, B0); PG8_MMA(1, 1, At, B1); PG8_BAR; PG8_SCHED;
	s_add_i32 s77, s77, s71
	v_lshl_add_u64 v[168:169], v[168:169], 0, s[54:55]
	s_mov_b32 m0, s77
	ds_read_b128 v[202:205], v175 offset:49152
	ds_read_b128 v[206:209], v175 offset:50176
	ds_read_b128 v[210:213], v175 offset:51200
	ds_read_b128 v[214:217], v175 offset:52224
	ds_read_b128 v[218:221], v175 offset:53248
	ds_read_b128 v[226:229], v175 offset:54272
	ds_read_b128 v[230:233], v175 offset:55296
	ds_read_b128 v[236:239], v175 offset:56320
	global_load_lds_dwordx4 v[168:169], off
	s_add_i32 m0, s77, 0x2000
	s_add_u32 s84, s84, 0x40080
	v_lshl_add_u64 v[168:169], v[178:179], 0, s[54:55]
	s_addc_u32 s85, s85, 0
	s_add_i32 s77, s88, s71
	global_load_lds_dwordx4 v[168:169], off
	v_lshl_add_u64 v[168:169], s[84:85], 0, v[142:143]
	s_mov_b32 m0, s77
	s_nop 0
	global_load_lds_dwordx4 v[168:169], off
	v_lshl_add_u64 v[244:245], s[84:85], 0, v[146:147]
	v_lshl_add_u64 v[246:247], v[222:223], 0, s[54:55]
	v_lshl_add_u64 v[168:169], v[240:241], 0, s[54:55]
	s_waitcnt vmcnt(5)
	s_waitcnt lgkmcnt(0)
	s_barrier
	s_setprio 1
	s_waitcnt lgkmcnt(0)
	v_mfma_f32_16x16x32_bf16 v[60:63], v[128:131], v[202:205], v[60:63]
	v_mfma_f32_16x16x32_bf16 v[52:55], v[136:139], v[202:205], v[52:55]
	v_mfma_f32_16x16x32_bf16 v[44:47], v[128:131], v[210:213], v[44:47]
	v_mfma_f32_16x16x32_bf16 v[36:39], v[136:139], v[210:213], v[36:39]
	s_add_i32 m0, s77, 0x2000
	v_mfma_f32_16x16x32_bf16 v[28:31], v[128:131], v[218:221], v[28:31]
	global_load_lds_dwordx4 v[244:245], off
	v_mfma_f32_16x16x32_bf16 v[20:23], v[136:139], v[218:221], v[20:23]
	v_mfma_f32_16x16x32_bf16 v[12:15], v[128:131], v[230:233], v[12:15]
	v_mfma_f32_16x16x32_bf16 v[4:7], v[136:139], v[230:233], v[4:7]
	v_mfma_f32_16x16x32_bf16 v[60:63], v[132:135], v[206:209], v[60:63]
	v_mfma_f32_16x16x32_bf16 v[52:55], v[182:185], v[206:209], v[52:55]
	v_mfma_f32_16x16x32_bf16 v[44:47], v[132:135], v[214:217], v[44:47]
	v_mfma_f32_16x16x32_bf16 v[36:39], v[182:185], v[214:217], v[36:39]
	s_mov_b32 m0, s33
	v_mfma_f32_16x16x32_bf16 v[28:31], v[132:135], v[226:229], v[28:31]
	global_load_lds_dwordx4 v[246:247], off
	v_mfma_f32_16x16x32_bf16 v[20:23], v[182:185], v[226:229], v[20:23]
	v_mfma_f32_16x16x32_bf16 v[12:15], v[132:135], v[236:239], v[12:15]
	v_mfma_f32_16x16x32_bf16 v[4:7], v[182:185], v[236:239], v[4:7]
	s_setprio 0
	s_setprio 1
	v_mfma_f32_16x16x32_bf16 v[56:59], v[186:189], v[202:205], v[56:59]
	v_mfma_f32_16x16x32_bf16 v[48:51], v[194:197], v[202:205], v[48:51]
	v_mfma_f32_16x16x32_bf16 v[40:43], v[186:189], v[210:213], v[40:43]
	v_mfma_f32_16x16x32_bf16 v[32:35], v[194:197], v[210:213], v[32:35]
	s_mov_b32 m0, s30
	v_mfma_f32_16x16x32_bf16 v[24:27], v[186:189], v[218:221], v[24:27]
	global_load_lds_dwordx4 v[168:169], off
	v_mfma_f32_16x16x32_bf16 v[16:19], v[194:197], v[218:221], v[16:19]
	v_mfma_f32_16x16x32_bf16 v[8:11], v[186:189], v[230:233], v[8:11]
	v_mfma_f32_16x16x32_bf16 v[0:3], v[194:197], v[230:233], v[0:3]
	v_mfma_f32_16x16x32_bf16 v[56:59], v[190:193], v[206:209], v[56:59]
	v_mfma_f32_16x16x32_bf16 v[48:51], v[198:201], v[206:209], v[48:51]
	v_mfma_f32_16x16x32_bf16 v[40:43], v[190:193], v[214:217], v[40:43]
	v_mfma_f32_16x16x32_bf16 v[32:35], v[198:201], v[214:217], v[32:35]
	v_mfma_f32_16x16x32_bf16 v[24:27], v[190:193], v[226:229], v[24:27]
	v_mfma_f32_16x16x32_bf16 v[16:19], v[198:201], v[226:229], v[16:19]
	v_mfma_f32_16x16x32_bf16 v[8:11], v[190:193], v[236:239], v[8:11]
	v_mfma_f32_16x16x32_bf16 v[0:3], v[198:201], v[236:239], v[0:3]
	s_setprio 0
	s_barrier
	s_add_i32 s75, s75, 2
	s_add_u32 s82, s82, 0x100
	s_addc_u32 s83, s83, 0
	s_add_u32 s44, s44, 0x100
	s_addc_u32 s45, s45, 0
	s_cmp_gt_u32 s75, 13
	s_cbranch_scc0 .LBB0_387
	s_and_b64 vcc, exec, s[56:57]
	s_cbranch_vccz .LBB0_390
	s_barrier

; #define PG8_STAGE(bufoff, gbase, voff) do { _Pragma("unroll") for (int _i = 0; _i < 2; ++_i) \
;         __builtin_amdgcn_global_load_lds((const unsigned*)((const char*)(gbase) + (voff)[_i]), (PG8_LAS unsigned*)(lds + (bufoff) + ldsw + _i * 8192), 16, 0, 0); } while (0)
; #define PG8_LDA(dst, b, h) do { _Pragma("unroll") for (int m = 0; m < 4; ++m) _Pragma("unroll") for (int k = 0; k < 2; ++k) dst[m][k] = *(const PG8_LAS bf16x8*)(lds + PG8_SA(b, h) + aoff + m * 2048 + k * 1024); } while (0)
; #define PG8_LDB(dst, b, h) do { _Pragma("unroll") for (int n = 0; n < 2; ++n) _Pragma("unroll") for (int k = 0; k < 2; ++k) dst[n][k] = *(const PG8_LAS bf16x8*)(lds + PG8_SB(b, h) + boff + n * 2048 + k * 1024); } while (0)
; #define PG8_MMA(ai, bj, At, Bt) do { __builtin_amdgcn_s_setprio(1); _Pragma("unroll") for (int m = 0; m < 4; ++m) _Pragma("unroll") for (int n = 0; n < 2; ++n) _Pragma("unroll") for (int k = 0; k < 2; ++k) \
;         acc[ai][bj][m][n] = __builtin_amdgcn_mfma_f32_16x16x32_bf16(Bt[n][k], At[m][k], acc[ai][bj][m][n], 0, 0, 0); __builtin_amdgcn_s_setprio(0); } while (0)
; #define PG8_WAIT_V(n) asm volatile("s_waitcnt vmcnt(" #n ")" ::: "memory")
; #define PG8_WAIT_L(n) asm volatile("s_waitcnt lgkmcnt(" #n ")" ::: "memory")
; #define PG8_BAR __builtin_amdgcn_s_barrier()
; #define PG8_SCHED __builtin_amdgcn_sched_barrier(0)
; template <class Epi, class Sched, bool ALIGN_EPI = false, bool SP2 = false>
; __device__ __forceinline__ void gemm_phase(PG8_LAS unsigned char* lds, const Gemm g, const Sched& S, const Epi& E) {
;     ...
;             PG8_LDB(B0, 0, 0); PG8_LDB(B1, 0, 1); PG8_SCHED; PG8_LDA(At, 0, 0); PG8_STAGE(PG8_SA(1, 1), a1 + hstep, voffA);
;             PG8_WAIT_V(8); PG8_WAIT_L(0); PG8_BAR; PG8_MMA(0, 0, At, B0); PG8_MMA(0, 1, At, B1); PG8_BAR; PG8_SCHED;
;             PG8_LDA(At, 0, 1); PG8_STAGE(PG8_SB(0, 0), b2, voffB); PG8_STAGE(PG8_SB(0, 1), b2 + hstep, voffB); PG8_STAGE(PG8_SA(0, 0), a2, voffA);
.LBB0_750:
	ds_read_b128 v[144:147], v151
	ds_read_b128 v[156:159], v151 offset:1024
	ds_read_b128 v[160:163], v151 offset:2048
	ds_read_b128 v[164:167], v151 offset:3072
	ds_read_b128 v[168:171], v152
	ds_read_b128 v[172:175], v152 offset:1024
	ds_read_b128 v[176:179], v152 offset:2048
	ds_read_b128 v[180:183], v152 offset:3072
	s_add_u32 s64, s62, 0xfffc0080
	s_addc_u32 s65, s63, -1
	s_cmp_eq_u32 s72, 12
	s_cselect_b32 s67, s19, s65
	s_cselect_b32 s66, s56, s64
	s_cselect_b32 s65, s17, s71
	s_cselect_b32 s64, s57, s61
	v_lshl_add_u64 v[216:217], s[62:63], 0, v[136:137]
	s_add_i32 m0, s22, 0xc000
	ds_read_b128 v[184:187], v153
	ds_read_b128 v[188:191], v153 offset:1024
	ds_read_b128 v[192:195], v153 offset:2048
	ds_read_b128 v[196:199], v153 offset:3072
	ds_read_b128 v[200:203], v153 offset:4096
	ds_read_b128 v[204:207], v153 offset:5120
	ds_read_b128 v[208:211], v153 offset:6144
	ds_read_b128 v[212:215], v153 offset:7168
	global_load_lds_dwordx4 v[216:217], off
	v_lshl_add_u64 v[216:217], s[62:63], 0, v[138:139]
	s_add_i32 m0, s22, 0xe000
	s_nop 0
	global_load_lds_dwordx4 v[216:217], off
	s_waitcnt vmcnt(8)
	s_waitcnt lgkmcnt(0)
	s_barrier
	s_setprio 1
	s_waitcnt lgkmcnt(0)
	v_mfma_f32_16x16x32_bf16 v[124:127], v[144:147], v[184:187], v[124:127]
	v_mfma_f32_16x16x32_bf16 v[120:123], v[160:163], v[184:187], v[120:123]
	v_mfma_f32_16x16x32_bf16 v[108:111], v[144:147], v[192:195], v[108:111]
	v_mfma_f32_16x16x32_bf16 v[104:107], v[160:163], v[192:195], v[104:107]
	v_mfma_f32_16x16x32_bf16 v[92:95], v[144:147], v[200:203], v[92:95]
	v_mfma_f32_16x16x32_bf16 v[88:91], v[160:163], v[200:203], v[88:91]
	v_mfma_f32_16x16x32_bf16 v[76:79], v[144:147], v[208:211], v[76:79]
	v_mfma_f32_16x16x32_bf16 v[72:75], v[160:163], v[208:211], v[72:75]
	v_mfma_f32_16x16x32_bf16 v[124:127], v[156:159], v[188:191], v[124:127]
	v_mfma_f32_16x16x32_bf16 v[120:123], v[164:167], v[188:191], v[120:123]
	v_mfma_f32_16x16x32_bf16 v[108:111], v[156:159], v[196:199], v[108:111]
	v_mfma_f32_16x16x32_bf16 v[104:107], v[164:167], v[196:199], v[104:107]
	v_mfma_f32_16x16x32_bf16 v[92:95], v[156:159], v[204:207], v[92:95]
	v_mfma_f32_16x16x32_bf16 v[88:91], v[164:167], v[204:207], v[88:91]
	v_mfma_f32_16x16x32_bf16 v[76:79], v[156:159], v[212:215], v[76:79]
	v_mfma_f32_16x16x32_bf16 v[72:75], v[164:167], v[212:215], v[72:75]
	s_setprio 0
	s_setprio 1
	v_mfma_f32_16x16x32_bf16 v[116:119], v[168:171], v[184:187], v[116:119]
	v_mfma_f32_16x16x32_bf16 v[112:115], v[176:179], v[184:187], v[112:115]
	v_mfma_f32_16x16x32_bf16 v[100:103], v[168:171], v[192:195], v[100:103]
	v_mfma_f32_16x16x32_bf16 v[96:99], v[176:179], v[192:195], v[96:99]
	v_mfma_f32_16x16x32_bf16 v[84:87], v[168:171], v[200:203], v[84:87]
	v_mfma_f32_16x16x32_bf16 v[80:83], v[176:179], v[200:203], v[80:83]
	v_mfma_f32_16x16x32_bf16 v[68:71], v[168:171], v[208:211], v[68:71]
	v_mfma_f32_16x16x32_bf16 v[64:67], v[176:179], v[208:211], v[64:67]
	v_mfma_f32_16x16x32_bf16 v[116:119], v[172:175], v[188:191], v[116:119]
	v_mfma_f32_16x16x32_bf16 v[112:115], v[180:183], v[188:191], v[112:115]
	v_mfma_f32_16x16x32_bf16 v[100:103], v[172:175], v[196:199], v[100:103]
	v_mfma_f32_16x16x32_bf16 v[96:99], v[180:183], v[196:199], v[96:99]
	v_mfma_f32_16x16x32_bf16 v[84:87], v[172:175], v[204:207], v[84:87]
	v_mfma_f32_16x16x32_bf16 v[80:83], v[180:183], v[204:207], v[80:83]
	v_mfma_f32_16x16x32_bf16 v[68:71], v[172:175], v[212:215], v[68:71]
	v_mfma_f32_16x16x32_bf16 v[64:67], v[180:183], v[212:215], v[64:67]
	s_setprio 0
	s_barrier
	s_add_i32 s73, s68, s2
	v_lshl_add_u64 v[216:217], s[64:65], 0, v[130:131]
	s_mov_b32 m0, s73
	ds_read_b128 v[184:187], v153 offset:16384
	ds_read_b128 v[188:191], v153 offset:17408
	ds_read_b128 v[192:195], v153 offset:18432
	ds_read_b128 v[196:199], v153 offset:19456
	ds_read_b128 v[200:203], v153 offset:20480
	ds_read_b128 v[204:207], v153 offset:21504
	ds_read_b128 v[208:211], v153 offset:22528
	ds_read_b128 v[212:215], v153 offset:23552
	global_load_lds_dwordx4 v[216:217], off
	s_add_i32 m0, s73, 0x2000
	s_add_u32 s74, s64, 0x40000
	v_lshl_add_u64 v[218:219], s[64:65], 0, v[134:135]
	s_addc_u32 s75, s65, 0
	s_add_i32 s73, s69, s2
	global_load_lds_dwordx4 v[218:219], off
	v_lshl_add_u64 v[220:221], s[74:75], 0, v[130:131]
	s_mov_b32 m0, s73
	v_lshl_add_u64 v[222:223], s[66:67], 0, v[132:133]
	global_load_lds_dwordx4 v[220:221], off
	v_lshl_add_u64 v[244:245], s[74:75], 0, v[134:135]
	v_lshl_add_u64 v[220:221], s[66:67], 0, v[128:129]
	s_waitcnt vmcnt(5)
	s_waitcnt lgkmcnt(0)
	s_barrier
; #define PG8_STAGE(bufoff, gbase, voff) do { _Pragma("unroll") for (int _i = 0; _i < 2; ++_i) \
;         __builtin_amdgcn_global_load_lds((const unsigned*)((const char*)(gbase) + (voff)[_i]), (PG8_LAS unsigned*)(lds + (bufoff) + ldsw + _i * 8192), 16, 0, 0); } while (0)
; #define PG8_LDA(dst, b, h) do { _Pragma("unroll") for (int m = 0; m < 4; ++m) _Pragma("unroll") for (int k = 0; k < 2; ++k) dst[m][k] = *(const PG8_LAS bf16x8*)(lds + PG8_SA(b, h) + aoff + m * 2048 + k * 1024); } while (0)
; #define PG8_LDB(dst, b, h) do { _Pragma("unroll") for (int n = 0; n < 2; ++n) _Pragma("unroll") for (int k = 0; k < 2; ++k) dst[n][k] = *(const PG8_LAS bf16x8*)(lds + PG8_SB(b, h) + boff + n * 2048 + k * 1024); } while (0)
; #define PG8_MMA(ai, bj, At, Bt) do { __builtin_amdgcn_s_setprio(1); _Pragma("unroll") for (int m = 0; m < 4; ++m) _Pragma("unroll") for (int n = 0; n < 2; ++n) _Pragma("unroll") for (int k = 0; k < 2; ++k) \
;         acc[ai][bj][m][n] = __builtin_amdgcn_mfma_f32_16x16x32_bf16(Bt[n][k], At[m][k], acc[ai][bj][m][n], 0, 0, 0); __builtin_amdgcn_s_setprio(0); } while (0)
; #define PG8_WAIT_V(n) asm volatile("s_waitcnt vmcnt(" #n ")" ::: "memory")
; #define PG8_WAIT_L(n) asm volatile("s_waitcnt lgkmcnt(" #n ")" ::: "memory")
; #define PG8_BAR __builtin_amdgcn_s_barrier()
; #define PG8_SCHED __builtin_amdgcn_sched_barrier(0)
; template <class Epi, class Sched, bool ALIGN_EPI = false, bool SP2 = false>
; __device__ __forceinline__ void gemm_phase(PG8_LAS unsigned char* lds, const Gemm g, const Sched& S, const Epi& E) {
;     ...
;             PG8_WAIT_V(8); PG8_WAIT_L(0); PG8_BAR; PG8_MMA(1, 0, At, B0); PG8_MMA(1, 1, At, B1); PG8_BAR; PG8_SCHED;
;             PG8_LDB(B0, 1, 0); PG8_LDB(B1, 1, 1); PG8_SCHED; PG8_LDA(At, 1, 0); PG8_STAGE(PG8_SA(0, 1), a2 + hstep, voffA);
;             PG8_WAIT_V(8); PG8_WAIT_L(0); PG8_BAR; PG8_MMA(0, 0, At, B0); PG8_MMA(0, 1, At, B1); PG8_BAR; PG8_SCHED;
	s_setprio 1
	s_waitcnt lgkmcnt(0)
	v_mfma_f32_16x16x32_bf16 v[60:63], v[144:147], v[184:187], v[60:63]
	v_mfma_f32_16x16x32_bf16 v[56:59], v[160:163], v[184:187], v[56:59]
	v_mfma_f32_16x16x32_bf16 v[44:47], v[144:147], v[192:195], v[44:47]
	v_mfma_f32_16x16x32_bf16 v[40:43], v[160:163], v[192:195], v[40:43]
	s_add_i32 m0, s73, 0x2000
	v_mfma_f32_16x16x32_bf16 v[28:31], v[144:147], v[200:203], v[28:31]
	global_load_lds_dwordx4 v[244:245], off
	v_mfma_f32_16x16x32_bf16 v[24:27], v[160:163], v[200:203], v[24:27]
	v_mfma_f32_16x16x32_bf16 v[12:15], v[144:147], v[208:211], v[12:15]
	v_mfma_f32_16x16x32_bf16 v[8:11], v[160:163], v[208:211], v[8:11]
	v_mfma_f32_16x16x32_bf16 v[60:63], v[156:159], v[188:191], v[60:63]
	v_mfma_f32_16x16x32_bf16 v[56:59], v[164:167], v[188:191], v[56:59]
	v_mfma_f32_16x16x32_bf16 v[44:47], v[156:159], v[196:199], v[44:47]
	v_mfma_f32_16x16x32_bf16 v[40:43], v[164:167], v[196:199], v[40:43]
	s_mov_b32 m0, s22
	v_mfma_f32_16x16x32_bf16 v[28:31], v[156:159], v[204:207], v[28:31]
	global_load_lds_dwordx4 v[220:221], off
	v_mfma_f32_16x16x32_bf16 v[24:27], v[164:167], v[204:207], v[24:27]
	v_mfma_f32_16x16x32_bf16 v[12:15], v[156:159], v[212:215], v[12:15]
	v_mfma_f32_16x16x32_bf16 v[8:11], v[164:167], v[212:215], v[8:11]
	s_setprio 0
	s_setprio 1
	v_mfma_f32_16x16x32_bf16 v[52:55], v[168:171], v[184:187], v[52:55]
	v_mfma_f32_16x16x32_bf16 v[48:51], v[176:179], v[184:187], v[48:51]
	v_mfma_f32_16x16x32_bf16 v[36:39], v[168:171], v[192:195], v[36:39]
	v_mfma_f32_16x16x32_bf16 v[32:35], v[176:179], v[192:195], v[32:35]
	s_mov_b32 m0, s23
	v_mfma_f32_16x16x32_bf16 v[20:23], v[168:171], v[200:203], v[20:23]
	global_load_lds_dwordx4 v[222:223], off
	v_mfma_f32_16x16x32_bf16 v[16:19], v[176:179], v[200:203], v[16:19]
	v_mfma_f32_16x16x32_bf16 v[4:7], v[168:171], v[208:211], v[4:7]
	v_mfma_f32_16x16x32_bf16 v[0:3], v[176:179], v[208:211], v[0:3]
	v_mfma_f32_16x16x32_bf16 v[52:55], v[172:175], v[188:191], v[52:55]
	v_mfma_f32_16x16x32_bf16 v[48:51], v[180:183], v[188:191], v[48:51]
	v_mfma_f32_16x16x32_bf16 v[36:39], v[172:175], v[196:199], v[36:39]
	v_mfma_f32_16x16x32_bf16 v[32:35], v[180:183], v[196:199], v[32:35]
	v_mfma_f32_16x16x32_bf16 v[20:23], v[172:175], v[204:207], v[20:23]
	v_mfma_f32_16x16x32_bf16 v[16:19], v[180:183], v[204:207], v[16:19]
	v_mfma_f32_16x16x32_bf16 v[4:7], v[172:175], v[212:215], v[4:7]
	v_mfma_f32_16x16x32_bf16 v[0:3], v[180:183], v[212:215], v[0:3]
	s_setprio 0
	s_barrier
	s_add_i32 s73, 0, 0x18000
	v_add_u32_e32 v155, s73, v149
	s_add_i32 s74, 0, 0x1c000
	ds_read_b128 v[144:147], v155
	ds_read_b128 v[156:159], v155 offset:1024
	ds_read_b128 v[160:163], v155 offset:2048
	ds_read_b128 v[164:167], v155 offset:3072
	v_add_u32_e32 v155, s74, v149
	ds_read_b128 v[168:171], v155
	ds_read_b128 v[172:175], v155 offset:1024
	ds_read_b128 v[176:179], v155 offset:2048
	ds_read_b128 v[180:183], v155 offset:3072
	s_add_u32 s66, s66, 0x40000
	s_addc_u32 s67, s67, 0
	s_mov_b32 m0, s30
	v_lshl_add_u64 v[226:227], s[66:67], 0, v[128:129]
	ds_read_b128 v[184:187], v153 offset:32768
	ds_read_b128 v[188:191], v153 offset:33792
	ds_read_b128 v[192:195], v153 offset:34816
	ds_read_b128 v[196:199], v153 offset:35840
	ds_read_b128 v[200:203], v153 offset:36864
	ds_read_b128 v[204:207], v153 offset:37888
	ds_read_b128 v[208:211], v153 offset:38912
	ds_read_b128 v[212:215], v153 offset:39936
	global_load_lds_dwordx4 v[226:227], off
	v_lshl_add_u64 v[226:227], s[66:67], 0, v[132:133]
	s_mov_b32 m0, s31
	s_nop 0
	global_load_lds_dwordx4 v[226:227], off
	s_waitcnt vmcnt(8)
	s_waitcnt lgkmcnt(0)
	s_barrier
	s_setprio 1
	s_waitcnt lgkmcnt(0)
	v_mfma_f32_16x16x32_bf16 v[124:127], v[144:147], v[184:187], v[124:127]
	v_mfma_f32_16x16x32_bf16 v[120:123], v[160:163], v[184:187], v[120:123]
	v_mfma_f32_16x16x32_bf16 v[108:111], v[144:147], v[192:195], v[108:111]
	v_mfma_f32_16x16x32_bf16 v[104:107], v[160:163], v[192:195], v[104:107]
	v_mfma_f32_16x16x32_bf16 v[92:95], v[144:147], v[200:203], v[92:95]
	v_mfma_f32_16x16x32_bf16 v[88:91], v[160:163], v[200:203], v[88:91]
	v_mfma_f32_16x16x32_bf16 v[76:79], v[144:147], v[208:211], v[76:79]
	v_mfma_f32_16x16x32_bf16 v[72:75], v[160:163], v[208:211], v[72:75]
	v_mfma_f32_16x16x32_bf16 v[124:127], v[156:159], v[188:191], v[124:127]
	v_mfma_f32_16x16x32_bf16 v[120:123], v[164:167], v[188:191], v[120:123]
	v_mfma_f32_16x16x32_bf16 v[108:111], v[156:159], v[196:199], v[108:111]
	v_mfma_f32_16x16x32_bf16 v[104:107], v[164:167], v[196:199], v[104:107]
	v_mfma_f32_16x16x32_bf16 v[92:95], v[156:159], v[204:207], v[92:95]
	v_mfma_f32_16x16x32_bf16 v[88:91], v[164:167], v[204:207], v[88:91]
	v_mfma_f32_16x16x32_bf16 v[76:79], v[156:159], v[212:215], v[76:79]
	v_mfma_f32_16x16x32_bf16 v[72:75], v[164:167], v[212:215], v[72:75]
	s_setprio 0
	s_setprio 1
	v_mfma_f32_16x16x32_bf16 v[116:119], v[168:171], v[184:187], v[116:119]
	v_mfma_f32_16x16x32_bf16 v[112:115], v[176:179], v[184:187], v[112:115]
	v_mfma_f32_16x16x32_bf16 v[100:103], v[168:171], v[192:195], v[100:103]
	v_mfma_f32_16x16x32_bf16 v[96:99], v[176:179], v[192:195], v[96:99]
	v_mfma_f32_16x16x32_bf16 v[84:87], v[168:171], v[200:203], v[84:87]
	v_mfma_f32_16x16x32_bf16 v[80:83], v[176:179], v[200:203], v[80:83]
	v_mfma_f32_16x16x32_bf16 v[68:71], v[168:171], v[208:211], v[68:71]
	v_mfma_f32_16x16x32_bf16 v[64:67], v[176:179], v[208:211], v[64:67]
	v_mfma_f32_16x16x32_bf16 v[116:119], v[172:175], v[188:191], v[116:119]
	v_mfma_f32_16x16x32_bf16 v[112:115], v[180:183], v[188:191], v[112:115]
	v_mfma_f32_16x16x32_bf16 v[100:103], v[172:175], v[196:199], v[100:103]
	v_mfma_f32_16x16x32_bf16 v[96:99], v[180:183], v[196:199], v[96:99]
	v_mfma_f32_16x16x32_bf16 v[84:87], v[172:175], v[204:207], v[84:87]
	v_mfma_f32_16x16x32_bf16 v[80:83], v[180:183], v[204:207], v[80:83]
	v_mfma_f32_16x16x32_bf16 v[68:71], v[172:175], v[212:215], v[68:71]
	v_mfma_f32_16x16x32_bf16 v[64:67], v[180:183], v[212:215], v[64:67]
	s_setprio 0
	s_barrier
; #define PG8_STAGE(bufoff, gbase, voff) do { _Pragma("unroll") for (int _i = 0; _i < 2; ++_i) \
;         __builtin_amdgcn_global_load_lds((const unsigned*)((const char*)(gbase) + (voff)[_i]), (PG8_LAS unsigned*)(lds + (bufoff) + ldsw + _i * 8192), 16, 0, 0); } while (0)
; #define PG8_LDA(dst, b, h) do { _Pragma("unroll") for (int m = 0; m < 4; ++m) _Pragma("unroll") for (int k = 0; k < 2; ++k) dst[m][k] = *(const PG8_LAS bf16x8*)(lds + PG8_SA(b, h) + aoff + m * 2048 + k * 1024); } while (0)
; #define PG8_MMA(ai, bj, At, Bt) do { __builtin_amdgcn_s_setprio(1); _Pragma("unroll") for (int m = 0; m < 4; ++m) _Pragma("unroll") for (int n = 0; n < 2; ++n) _Pragma("unroll") for (int k = 0; k < 2; ++k) \
;         acc[ai][bj][m][n] = __builtin_amdgcn_mfma_f32_16x16x32_bf16(Bt[n][k], At[m][k], acc[ai][bj][m][n], 0, 0, 0); __builtin_amdgcn_s_setprio(0); } while (0)
; #define PG8_WAIT_V(n) asm volatile("s_waitcnt vmcnt(" #n ")" ::: "memory")
; #define PG8_WAIT_L(n) asm volatile("s_waitcnt lgkmcnt(" #n ")" ::: "memory")
; #define PG8_BAR __builtin_amdgcn_s_barrier()
; #define PG8_SCHED __builtin_amdgcn_sched_barrier(0)
; template <class Epi, class Sched, bool ALIGN_EPI = false, bool SP2 = false>
; __device__ __forceinline__ void gemm_phase(PG8_LAS unsigned char* lds, const Gemm g, const Sched& S, const Epi& E) {
;     ...
;         for (int t = 0; t < nt; t += 2) {
;             const bool last = (t == nt - 2);
;             const char* a1 = cA + (size_t)(t + 1) * kstep;
;             const char* a2 = last ? nA : cA + (size_t)(t + 2) * kstep; const char* b2 = last ? nB : cB + (size_t)(t + 2) * kstep;
;             const char* a3 = a2 + kstep; const char* b3 = b2 + kstep;
;     ...
;             PG8_LDA(At, 1, 1); PG8_STAGE(PG8_SB(1, 0), b3, voffB); PG8_STAGE(PG8_SB(1, 1), b3 + hstep, voffB); PG8_STAGE(PG8_SA(1, 0), a3, voffA);
;             PG8_WAIT_V(8); PG8_WAIT_L(0); PG8_BAR; PG8_MMA(1, 0, At, B0); PG8_MMA(1, 1, At, B1); PG8_BAR; PG8_SCHED;
	s_add_i32 s66, s73, s2
	v_lshl_add_u64 v[216:217], v[216:217], 0, s[12:13]
	s_mov_b32 m0, s66
	ds_read_b128 v[184:187], v153 offset:49152
	ds_read_b128 v[188:191], v153 offset:50176
	ds_read_b128 v[192:195], v153 offset:51200
	ds_read_b128 v[196:199], v153 offset:52224
	ds_read_b128 v[200:203], v153 offset:53248
	ds_read_b128 v[204:207], v153 offset:54272
	ds_read_b128 v[208:211], v153 offset:55296
	ds_read_b128 v[212:215], v153 offset:56320
	global_load_lds_dwordx4 v[216:217], off
	s_add_i32 m0, s66, 0x2000
	s_add_u32 s64, s64, 0x40080
	v_lshl_add_u64 v[216:217], v[218:219], 0, s[12:13]
	s_addc_u32 s65, s65, 0
	s_add_i32 s66, s74, s2
	global_load_lds_dwordx4 v[216:217], off
	v_lshl_add_u64 v[216:217], s[64:65], 0, v[130:131]
	s_mov_b32 m0, s66
	s_nop 0
	global_load_lds_dwordx4 v[216:217], off
	v_lshl_add_u64 v[244:245], s[64:65], 0, v[134:135]
	v_lshl_add_u64 v[246:247], v[220:221], 0, s[12:13]
	v_lshl_add_u64 v[216:217], v[222:223], 0, s[12:13]
	s_waitcnt vmcnt(5)
	s_waitcnt lgkmcnt(0)
	s_barrier
	s_setprio 1
	s_waitcnt lgkmcnt(0)
	v_mfma_f32_16x16x32_bf16 v[60:63], v[144:147], v[184:187], v[60:63]
	v_mfma_f32_16x16x32_bf16 v[56:59], v[160:163], v[184:187], v[56:59]
	v_mfma_f32_16x16x32_bf16 v[44:47], v[144:147], v[192:195], v[44:47]
	v_mfma_f32_16x16x32_bf16 v[40:43], v[160:163], v[192:195], v[40:43]
	s_add_i32 m0, s66, 0x2000
	v_mfma_f32_16x16x32_bf16 v[28:31], v[144:147], v[200:203], v[28:31]
	global_load_lds_dwordx4 v[244:245], off
	v_mfma_f32_16x16x32_bf16 v[24:27], v[160:163], v[200:203], v[24:27]
	v_mfma_f32_16x16x32_bf16 v[12:15], v[144:147], v[208:211], v[12:15]
	v_mfma_f32_16x16x32_bf16 v[8:11], v[160:163], v[208:211], v[8:11]
	v_mfma_f32_16x16x32_bf16 v[60:63], v[156:159], v[188:191], v[60:63]
	v_mfma_f32_16x16x32_bf16 v[56:59], v[164:167], v[188:191], v[56:59]
	v_mfma_f32_16x16x32_bf16 v[44:47], v[156:159], v[196:199], v[44:47]
	v_mfma_f32_16x16x32_bf16 v[40:43], v[164:167], v[196:199], v[40:43]
	s_mov_b32 m0, s44
	v_mfma_f32_16x16x32_bf16 v[28:31], v[156:159], v[204:207], v[28:31]
	global_load_lds_dwordx4 v[246:247], off
	v_mfma_f32_16x16x32_bf16 v[24:27], v[164:167], v[204:207], v[24:27]
	v_mfma_f32_16x16x32_bf16 v[12:15], v[156:159], v[212:215], v[12:15]
	v_mfma_f32_16x16x32_bf16 v[8:11], v[164:167], v[212:215], v[8:11]
	s_setprio 0
	s_setprio 1
	v_mfma_f32_16x16x32_bf16 v[52:55], v[168:171], v[184:187], v[52:55]
	v_mfma_f32_16x16x32_bf16 v[48:51], v[176:179], v[184:187], v[48:51]
	v_mfma_f32_16x16x32_bf16 v[36:39], v[168:171], v[192:195], v[36:39]
	v_mfma_f32_16x16x32_bf16 v[32:35], v[176:179], v[192:195], v[32:35]
	s_mov_b32 m0, s45
	v_mfma_f32_16x16x32_bf16 v[20:23], v[168:171], v[200:203], v[20:23]
	global_load_lds_dwordx4 v[216:217], off
	v_mfma_f32_16x16x32_bf16 v[16:19], v[176:179], v[200:203], v[16:19]
	v_mfma_f32_16x16x32_bf16 v[4:7], v[168:171], v[208:211], v[4:7]
	v_mfma_f32_16x16x32_bf16 v[0:3], v[176:179], v[208:211], v[0:3]
	v_mfma_f32_16x16x32_bf16 v[52:55], v[172:175], v[188:191], v[52:55]
	v_mfma_f32_16x16x32_bf16 v[48:51], v[180:183], v[188:191], v[48:51]
	v_mfma_f32_16x16x32_bf16 v[36:39], v[172:175], v[196:199], v[36:39]
	v_mfma_f32_16x16x32_bf16 v[32:35], v[180:183], v[196:199], v[32:35]
	v_mfma_f32_16x16x32_bf16 v[20:23], v[172:175], v[204:207], v[20:23]
	v_mfma_f32_16x16x32_bf16 v[16:19], v[180:183], v[204:207], v[16:19]
	v_mfma_f32_16x16x32_bf16 v[4:7], v[172:175], v[212:215], v[4:7]
	v_mfma_f32_16x16x32_bf16 v[0:3], v[180:183], v[212:215], v[0:3]
	s_setprio 0
	s_barrier
	s_add_i32 s72, s72, 2
	s_add_u32 s62, s62, 0x100
	s_addc_u32 s63, s63, 0
	s_add_u32 s61, s61, 0x100
	s_addc_u32 s71, s71, 0
	s_cmp_gt_u32 s72, 13
	s_cbranch_scc0 .LBB0_750
	s_and_b64 vcc, exec, s[14:15]
	s_cbranch_vccz .LBB0_753
	s_barrier

; #define PG8_STAGE(bufoff, gbase, voff) do { _Pragma("unroll") for (int _i = 0; _i < 2; ++_i) \
;         __builtin_amdgcn_global_load_lds((const unsigned*)((const char*)(gbase) + (voff)[_i]), (PG8_LAS unsigned*)(lds + (bufoff) + ldsw + _i * 8192), 16, 0, 0); } while (0)
; #define PG8_LDA(dst, b, h) do { _Pragma("unroll") for (int m = 0; m < 4; ++m) _Pragma("unroll") for (int k = 0; k < 2; ++k) dst[m][k] = *(const PG8_LAS bf16x8*)(lds + PG8_SA(b, h) + aoff + m * 2048 + k * 1024); } while (0)
; #define PG8_LDB(dst, b, h) do { _Pragma("unroll") for (int n = 0; n < 2; ++n) _Pragma("unroll") for (int k = 0; k < 2; ++k) dst[n][k] = *(const PG8_LAS bf16x8*)(lds + PG8_SB(b, h) + boff + n * 2048 + k * 1024); } while (0)
; #define PG8_MMA(ai, bj, At, Bt) do { __builtin_amdgcn_s_setprio(1); _Pragma("unroll") for (int m = 0; m < 4; ++m) _Pragma("unroll") for (int n = 0; n < 2; ++n) _Pragma("unroll") for (int k = 0; k < 2; ++k) \
;         acc[ai][bj][m][n] = __builtin_amdgcn_mfma_f32_16x16x32_bf16(Bt[n][k], At[m][k], acc[ai][bj][m][n], 0, 0, 0); __builtin_amdgcn_s_setprio(0); } while (0)
; #define PG8_WAIT_V(n) asm volatile("s_waitcnt vmcnt(" #n ")" ::: "memory")
; #define PG8_WAIT_L(n) asm volatile("s_waitcnt lgkmcnt(" #n ")" ::: "memory")
; #define PG8_BAR __builtin_amdgcn_s_barrier()
; #define PG8_SCHED __builtin_amdgcn_sched_barrier(0)
; template <class Epi, class Sched, bool ALIGN_EPI = false, bool SP2 = false>
; __device__ __forceinline__ void gemm_phase(PG8_LAS unsigned char* lds, const Gemm g, const Sched& S, const Epi& E) {
;     ...
;             PG8_LDB(B0, 0, 0); PG8_LDB(B1, 0, 1); PG8_SCHED; PG8_LDA(At, 0, 0); PG8_STAGE(PG8_SA(1, 1), a1 + hstep, voffA);
;             PG8_WAIT_V(8); PG8_WAIT_L(0); PG8_BAR; PG8_MMA(0, 0, At, B0); PG8_MMA(0, 1, At, B1); PG8_BAR; PG8_SCHED;
;             PG8_LDA(At, 0, 1); PG8_STAGE(PG8_SB(0, 0), b2, voffB); PG8_STAGE(PG8_SB(0, 1), b2 + hstep, voffB); PG8_STAGE(PG8_SA(0, 0), a2, voffA);
.LBB0_835:
	ds_read_b128 v[128:131], v226
	ds_read_b128 v[158:161], v226 offset:1024
	ds_read_b128 v[162:165], v226 offset:2048
	ds_read_b128 v[166:169], v226 offset:3072
	ds_read_b128 v[170:173], v227
	ds_read_b128 v[174:177], v227 offset:1024
	ds_read_b128 v[178:181], v227 offset:2048
	ds_read_b128 v[182:185], v227 offset:3072
	s_add_u32 s8, s6, 0xfffc0080
	s_addc_u32 s9, s7, -1
	s_cmp_eq_u32 s80, 12
	s_cselect_b32 s79, s5, s9
	s_cselect_b32 s78, s12, s8
	s_cselect_b32 s9, s56, s73
	s_cselect_b32 s8, s57, s71
	v_lshl_add_u64 v[218:219], s[6:7], 0, v[150:151]
	s_add_i32 m0, s30, 0xc000
	ds_read_b128 v[186:189], v228
	ds_read_b128 v[190:193], v228 offset:1024
	ds_read_b128 v[194:197], v228 offset:2048
	ds_read_b128 v[198:201], v228 offset:3072
	ds_read_b128 v[202:205], v228 offset:4096
	ds_read_b128 v[206:209], v228 offset:5120
	ds_read_b128 v[210:213], v228 offset:6144
	ds_read_b128 v[214:217], v228 offset:7168
	global_load_lds_dwordx4 v[218:219], off
	v_lshl_add_u64 v[218:219], s[6:7], 0, v[152:153]
	s_add_i32 m0, s30, 0xe000
	s_nop 0
	global_load_lds_dwordx4 v[218:219], off
	s_waitcnt vmcnt(8)
	s_waitcnt lgkmcnt(0)
	s_barrier
	s_setprio 1
	s_waitcnt lgkmcnt(0)
	v_mfma_f32_16x16x32_bf16 v[124:127], v[128:131], v[186:189], v[124:127]
	v_mfma_f32_16x16x32_bf16 v[120:123], v[162:165], v[186:189], v[120:123]
	v_mfma_f32_16x16x32_bf16 v[108:111], v[128:131], v[194:197], v[108:111]
	v_mfma_f32_16x16x32_bf16 v[100:103], v[162:165], v[194:197], v[100:103]
	v_mfma_f32_16x16x32_bf16 v[92:95], v[128:131], v[202:205], v[92:95]
	v_mfma_f32_16x16x32_bf16 v[88:91], v[162:165], v[202:205], v[88:91]
	v_mfma_f32_16x16x32_bf16 v[76:79], v[128:131], v[210:213], v[76:79]
	v_mfma_f32_16x16x32_bf16 v[72:75], v[162:165], v[210:213], v[72:75]
	v_mfma_f32_16x16x32_bf16 v[124:127], v[158:161], v[190:193], v[124:127]
	v_mfma_f32_16x16x32_bf16 v[120:123], v[166:169], v[190:193], v[120:123]
	v_mfma_f32_16x16x32_bf16 v[108:111], v[158:161], v[198:201], v[108:111]
	v_mfma_f32_16x16x32_bf16 v[100:103], v[166:169], v[198:201], v[100:103]
	v_mfma_f32_16x16x32_bf16 v[92:95], v[158:161], v[206:209], v[92:95]
	v_mfma_f32_16x16x32_bf16 v[88:91], v[166:169], v[206:209], v[88:91]
	v_mfma_f32_16x16x32_bf16 v[76:79], v[158:161], v[214:217], v[76:79]
	v_mfma_f32_16x16x32_bf16 v[72:75], v[166:169], v[214:217], v[72:75]
	s_setprio 0
	s_setprio 1
	v_mfma_f32_16x16x32_bf16 v[116:119], v[170:173], v[186:189], v[116:119]
	v_mfma_f32_16x16x32_bf16 v[112:115], v[178:181], v[186:189], v[112:115]
	v_mfma_f32_16x16x32_bf16 v[104:107], v[170:173], v[194:197], v[104:107]
	v_mfma_f32_16x16x32_bf16 v[96:99], v[178:181], v[194:197], v[96:99]
	v_mfma_f32_16x16x32_bf16 v[84:87], v[170:173], v[202:205], v[84:87]
	v_mfma_f32_16x16x32_bf16 v[80:83], v[178:181], v[202:205], v[80:83]
	v_mfma_f32_16x16x32_bf16 v[68:71], v[170:173], v[210:213], v[68:71]
	v_mfma_f32_16x16x32_bf16 v[64:67], v[178:181], v[210:213], v[64:67]
	v_mfma_f32_16x16x32_bf16 v[116:119], v[174:177], v[190:193], v[116:119]
	v_mfma_f32_16x16x32_bf16 v[112:115], v[182:185], v[190:193], v[112:115]
	v_mfma_f32_16x16x32_bf16 v[104:107], v[174:177], v[198:201], v[104:107]
	v_mfma_f32_16x16x32_bf16 v[96:99], v[182:185], v[198:201], v[96:99]
	v_mfma_f32_16x16x32_bf16 v[84:87], v[174:177], v[206:209], v[84:87]
	v_mfma_f32_16x16x32_bf16 v[80:83], v[182:185], v[206:209], v[80:83]
	v_mfma_f32_16x16x32_bf16 v[68:71], v[174:177], v[214:217], v[68:71]
	v_mfma_f32_16x16x32_bf16 v[64:67], v[182:185], v[214:217], v[64:67]
	s_setprio 0
	s_barrier
	s_add_i32 s81, s89, s22
	v_lshl_add_u64 v[218:219], s[8:9], 0, v[136:137]
	s_mov_b32 m0, s81
	ds_read_b128 v[186:189], v228 offset:16384
	ds_read_b128 v[190:193], v228 offset:17408
	ds_read_b128 v[194:197], v228 offset:18432
	ds_read_b128 v[198:201], v228 offset:19456
	ds_read_b128 v[202:205], v228 offset:20480
	ds_read_b128 v[206:209], v228 offset:21504
	ds_read_b128 v[210:213], v228 offset:22528
	ds_read_b128 v[214:217], v228 offset:23552
	global_load_lds_dwordx4 v[218:219], off
	s_add_i32 m0, s81, 0x2000
	s_add_u32 s82, s8, 0x40000
	v_lshl_add_u64 v[220:221], s[8:9], 0, v[132:133]
	s_addc_u32 s83, s9, 0
	s_add_i32 s81, s90, s22
	global_load_lds_dwordx4 v[220:221], off
	v_lshl_add_u64 v[222:223], s[82:83], 0, v[136:137]
	s_mov_b32 m0, s81
	v_lshl_add_u64 v[230:231], s[78:79], 0, v[134:135]
	global_load_lds_dwordx4 v[222:223], off
	v_lshl_add_u64 v[244:245], s[82:83], 0, v[132:133]
	v_lshl_add_u64 v[222:223], s[78:79], 0, v[138:139]
	s_waitcnt vmcnt(5)
	s_waitcnt lgkmcnt(0)
	s_barrier
; #define PG8_STAGE(bufoff, gbase, voff) do { _Pragma("unroll") for (int _i = 0; _i < 2; ++_i) \
;         __builtin_amdgcn_global_load_lds((const unsigned*)((const char*)(gbase) + (voff)[_i]), (PG8_LAS unsigned*)(lds + (bufoff) + ldsw + _i * 8192), 16, 0, 0); } while (0)
; #define PG8_LDA(dst, b, h) do { _Pragma("unroll") for (int m = 0; m < 4; ++m) _Pragma("unroll") for (int k = 0; k < 2; ++k) dst[m][k] = *(const PG8_LAS bf16x8*)(lds + PG8_SA(b, h) + aoff + m * 2048 + k * 1024); } while (0)
; #define PG8_LDB(dst, b, h) do { _Pragma("unroll") for (int n = 0; n < 2; ++n) _Pragma("unroll") for (int k = 0; k < 2; ++k) dst[n][k] = *(const PG8_LAS bf16x8*)(lds + PG8_SB(b, h) + boff + n * 2048 + k * 1024); } while (0)
; #define PG8_MMA(ai, bj, At, Bt) do { __builtin_amdgcn_s_setprio(1); _Pragma("unroll") for (int m = 0; m < 4; ++m) _Pragma("unroll") for (int n = 0; n < 2; ++n) _Pragma("unroll") for (int k = 0; k < 2; ++k) \
;         acc[ai][bj][m][n] = __builtin_amdgcn_mfma_f32_16x16x32_bf16(Bt[n][k], At[m][k], acc[ai][bj][m][n], 0, 0, 0); __builtin_amdgcn_s_setprio(0); } while (0)
; #define PG8_WAIT_V(n) asm volatile("s_waitcnt vmcnt(" #n ")" ::: "memory")
; #define PG8_WAIT_L(n) asm volatile("s_waitcnt lgkmcnt(" #n ")" ::: "memory")
; #define PG8_BAR __builtin_amdgcn_s_barrier()
; #define PG8_SCHED __builtin_amdgcn_sched_barrier(0)
; template <class Epi, class Sched, bool ALIGN_EPI = false, bool SP2 = false>
; __device__ __forceinline__ void gemm_phase(PG8_LAS unsigned char* lds, const Gemm g, const Sched& S, const Epi& E) {
;     ...
;             PG8_WAIT_V(8); PG8_WAIT_L(0); PG8_BAR; PG8_MMA(1, 0, At, B0); PG8_MMA(1, 1, At, B1); PG8_BAR; PG8_SCHED;
;             PG8_LDB(B0, 1, 0); PG8_LDB(B1, 1, 1); PG8_SCHED; PG8_LDA(At, 1, 0); PG8_STAGE(PG8_SA(0, 1), a2 + hstep, voffA);
;             PG8_WAIT_V(8); PG8_WAIT_L(0); PG8_BAR; PG8_MMA(0, 0, At, B0); PG8_MMA(0, 1, At, B1); PG8_BAR; PG8_SCHED;
	s_setprio 1
	s_waitcnt lgkmcnt(0)
	v_mfma_f32_16x16x32_bf16 v[60:63], v[128:131], v[186:189], v[60:63]
	v_mfma_f32_16x16x32_bf16 v[56:59], v[162:165], v[186:189], v[56:59]
	v_mfma_f32_16x16x32_bf16 v[44:47], v[128:131], v[194:197], v[44:47]
	v_mfma_f32_16x16x32_bf16 v[40:43], v[162:165], v[194:197], v[40:43]
	s_add_i32 m0, s81, 0x2000
	v_mfma_f32_16x16x32_bf16 v[28:31], v[128:131], v[202:205], v[28:31]
	global_load_lds_dwordx4 v[244:245], off
	v_mfma_f32_16x16x32_bf16 v[24:27], v[162:165], v[202:205], v[24:27]
	v_mfma_f32_16x16x32_bf16 v[12:15], v[128:131], v[210:213], v[12:15]
	v_mfma_f32_16x16x32_bf16 v[8:11], v[162:165], v[210:213], v[8:11]
	v_mfma_f32_16x16x32_bf16 v[60:63], v[158:161], v[190:193], v[60:63]
	v_mfma_f32_16x16x32_bf16 v[56:59], v[166:169], v[190:193], v[56:59]
	v_mfma_f32_16x16x32_bf16 v[44:47], v[158:161], v[198:201], v[44:47]
	v_mfma_f32_16x16x32_bf16 v[40:43], v[166:169], v[198:201], v[40:43]
	s_mov_b32 m0, s30
	v_mfma_f32_16x16x32_bf16 v[28:31], v[158:161], v[206:209], v[28:31]
	global_load_lds_dwordx4 v[222:223], off
	v_mfma_f32_16x16x32_bf16 v[24:27], v[166:169], v[206:209], v[24:27]
	v_mfma_f32_16x16x32_bf16 v[12:15], v[158:161], v[214:217], v[12:15]
	v_mfma_f32_16x16x32_bf16 v[8:11], v[166:169], v[214:217], v[8:11]
	s_setprio 0
	s_setprio 1
	v_mfma_f32_16x16x32_bf16 v[52:55], v[170:173], v[186:189], v[52:55]
	v_mfma_f32_16x16x32_bf16 v[48:51], v[178:181], v[186:189], v[48:51]
	v_mfma_f32_16x16x32_bf16 v[36:39], v[170:173], v[194:197], v[36:39]
	v_mfma_f32_16x16x32_bf16 v[32:35], v[178:181], v[194:197], v[32:35]
	s_mov_b32 m0, s31
	v_mfma_f32_16x16x32_bf16 v[20:23], v[170:173], v[202:205], v[20:23]
	global_load_lds_dwordx4 v[230:231], off
	v_mfma_f32_16x16x32_bf16 v[16:19], v[178:181], v[202:205], v[16:19]
	v_mfma_f32_16x16x32_bf16 v[4:7], v[170:173], v[210:213], v[4:7]
	v_mfma_f32_16x16x32_bf16 v[0:3], v[178:181], v[210:213], v[0:3]
	v_mfma_f32_16x16x32_bf16 v[52:55], v[174:177], v[190:193], v[52:55]
	v_mfma_f32_16x16x32_bf16 v[48:51], v[182:185], v[190:193], v[48:51]
	v_mfma_f32_16x16x32_bf16 v[36:39], v[174:177], v[198:201], v[36:39]
	v_mfma_f32_16x16x32_bf16 v[32:35], v[182:185], v[198:201], v[32:35]
	v_mfma_f32_16x16x32_bf16 v[20:23], v[174:177], v[206:209], v[20:23]
	v_mfma_f32_16x16x32_bf16 v[16:19], v[182:185], v[206:209], v[16:19]
	v_mfma_f32_16x16x32_bf16 v[4:7], v[174:177], v[214:217], v[4:7]
	v_mfma_f32_16x16x32_bf16 v[0:3], v[182:185], v[214:217], v[0:3]
	s_setprio 0
	s_barrier
	s_add_i32 s81, 0, 0x18000
	v_add_u32_e32 v140, s81, v225
	s_add_i32 s82, 0, 0x1c000
	ds_read_b128 v[128:131], v140
	ds_read_b128 v[158:161], v140 offset:1024
	ds_read_b128 v[162:165], v140 offset:2048
	ds_read_b128 v[166:169], v140 offset:3072
	v_add_u32_e32 v140, s82, v225
	ds_read_b128 v[170:173], v140
	ds_read_b128 v[174:177], v140 offset:1024
	ds_read_b128 v[178:181], v140 offset:2048
	ds_read_b128 v[182:185], v140 offset:3072
	s_add_u32 s78, s78, 0x40000
	s_addc_u32 s79, s79, 0
	s_mov_b32 m0, s33
	v_lshl_add_u64 v[232:233], s[78:79], 0, v[138:139]
	ds_read_b128 v[186:189], v228 offset:32768
	ds_read_b128 v[190:193], v228 offset:33792
	ds_read_b128 v[194:197], v228 offset:34816
	ds_read_b128 v[198:201], v228 offset:35840
	ds_read_b128 v[202:205], v228 offset:36864
	ds_read_b128 v[206:209], v228 offset:37888
	ds_read_b128 v[210:213], v228 offset:38912
	ds_read_b128 v[214:217], v228 offset:39936
	global_load_lds_dwordx4 v[232:233], off
	v_lshl_add_u64 v[232:233], s[78:79], 0, v[134:135]
	s_mov_b32 m0, s53
	s_nop 0
	global_load_lds_dwordx4 v[232:233], off
	s_waitcnt vmcnt(8)
	s_waitcnt lgkmcnt(0)
	s_barrier
	s_setprio 1
	s_waitcnt lgkmcnt(0)
	v_mfma_f32_16x16x32_bf16 v[124:127], v[128:131], v[186:189], v[124:127]
	v_mfma_f32_16x16x32_bf16 v[120:123], v[162:165], v[186:189], v[120:123]
	v_mfma_f32_16x16x32_bf16 v[108:111], v[128:131], v[194:197], v[108:111]
	v_mfma_f32_16x16x32_bf16 v[100:103], v[162:165], v[194:197], v[100:103]
	v_mfma_f32_16x16x32_bf16 v[92:95], v[128:131], v[202:205], v[92:95]
	v_mfma_f32_16x16x32_bf16 v[88:91], v[162:165], v[202:205], v[88:91]
	v_mfma_f32_16x16x32_bf16 v[76:79], v[128:131], v[210:213], v[76:79]
	v_mfma_f32_16x16x32_bf16 v[72:75], v[162:165], v[210:213], v[72:75]
	v_mfma_f32_16x16x32_bf16 v[124:127], v[158:161], v[190:193], v[124:127]
	v_mfma_f32_16x16x32_bf16 v[120:123], v[166:169], v[190:193], v[120:123]
	v_mfma_f32_16x16x32_bf16 v[108:111], v[158:161], v[198:201], v[108:111]
	v_mfma_f32_16x16x32_bf16 v[100:103], v[166:169], v[198:201], v[100:103]
	v_mfma_f32_16x16x32_bf16 v[92:95], v[158:161], v[206:209], v[92:95]
	v_mfma_f32_16x16x32_bf16 v[88:91], v[166:169], v[206:209], v[88:91]
	v_mfma_f32_16x16x32_bf16 v[76:79], v[158:161], v[214:217], v[76:79]
	v_mfma_f32_16x16x32_bf16 v[72:75], v[166:169], v[214:217], v[72:75]
	s_setprio 0
	s_setprio 1
	v_mfma_f32_16x16x32_bf16 v[116:119], v[170:173], v[186:189], v[116:119]
	v_mfma_f32_16x16x32_bf16 v[112:115], v[178:181], v[186:189], v[112:115]
	v_mfma_f32_16x16x32_bf16 v[104:107], v[170:173], v[194:197], v[104:107]
	v_mfma_f32_16x16x32_bf16 v[96:99], v[178:181], v[194:197], v[96:99]
	v_mfma_f32_16x16x32_bf16 v[84:87], v[170:173], v[202:205], v[84:87]
	v_mfma_f32_16x16x32_bf16 v[80:83], v[178:181], v[202:205], v[80:83]
	v_mfma_f32_16x16x32_bf16 v[68:71], v[170:173], v[210:213], v[68:71]
	v_mfma_f32_16x16x32_bf16 v[64:67], v[178:181], v[210:213], v[64:67]
	v_mfma_f32_16x16x32_bf16 v[116:119], v[174:177], v[190:193], v[116:119]
	v_mfma_f32_16x16x32_bf16 v[112:115], v[182:185], v[190:193], v[112:115]
	v_mfma_f32_16x16x32_bf16 v[104:107], v[174:177], v[198:201], v[104:107]
	v_mfma_f32_16x16x32_bf16 v[96:99], v[182:185], v[198:201], v[96:99]
	v_mfma_f32_16x16x32_bf16 v[84:87], v[174:177], v[206:209], v[84:87]
	v_mfma_f32_16x16x32_bf16 v[80:83], v[182:185], v[206:209], v[80:83]
	v_mfma_f32_16x16x32_bf16 v[68:71], v[174:177], v[214:217], v[68:71]
	v_mfma_f32_16x16x32_bf16 v[64:67], v[182:185], v[214:217], v[64:67]
	s_setprio 0
	s_barrier
; #define PG8_STAGE(bufoff, gbase, voff) do { _Pragma("unroll") for (int _i = 0; _i < 2; ++_i) \
;         __builtin_amdgcn_global_load_lds((const unsigned*)((const char*)(gbase) + (voff)[_i]), (PG8_LAS unsigned*)(lds + (bufoff) + ldsw + _i * 8192), 16, 0, 0); } while (0)
; #define PG8_LDA(dst, b, h) do { _Pragma("unroll") for (int m = 0; m < 4; ++m) _Pragma("unroll") for (int k = 0; k < 2; ++k) dst[m][k] = *(const PG8_LAS bf16x8*)(lds + PG8_SA(b, h) + aoff + m * 2048 + k * 1024); } while (0)
; #define PG8_MMA(ai, bj, At, Bt) do { __builtin_amdgcn_s_setprio(1); _Pragma("unroll") for (int m = 0; m < 4; ++m) _Pragma("unroll") for (int n = 0; n < 2; ++n) _Pragma("unroll") for (int k = 0; k < 2; ++k) \
;         acc[ai][bj][m][n] = __builtin_amdgcn_mfma_f32_16x16x32_bf16(Bt[n][k], At[m][k], acc[ai][bj][m][n], 0, 0, 0); __builtin_amdgcn_s_setprio(0); } while (0)
; #define PG8_WAIT_V(n) asm volatile("s_waitcnt vmcnt(" #n ")" ::: "memory")
; #define PG8_WAIT_L(n) asm volatile("s_waitcnt lgkmcnt(" #n ")" ::: "memory")
; #define PG8_BAR __builtin_amdgcn_s_barrier()
; #define PG8_SCHED __builtin_amdgcn_sched_barrier(0)
; template <class Epi, class Sched, bool ALIGN_EPI = false, bool SP2 = false>
; __device__ __forceinline__ void gemm_phase(PG8_LAS unsigned char* lds, const Gemm g, const Sched& S, const Epi& E) {
;     ...
;         for (int t = 0; t < nt; t += 2) {
;             const bool last = (t == nt - 2);
;             const char* a1 = cA + (size_t)(t + 1) * kstep;
;             const char* a2 = last ? nA : cA + (size_t)(t + 2) * kstep; const char* b2 = last ? nB : cB + (size_t)(t + 2) * kstep;
;             const char* a3 = a2 + kstep; const char* b3 = b2 + kstep;
;     ...
;             PG8_LDA(At, 1, 1); PG8_STAGE(PG8_SB(1, 0), b3, voffB); PG8_STAGE(PG8_SB(1, 1), b3 + hstep, voffB); PG8_STAGE(PG8_SA(1, 0), a3, voffA);
;             PG8_WAIT_V(8); PG8_WAIT_L(0); PG8_BAR; PG8_MMA(1, 0, At, B0); PG8_MMA(1, 1, At, B1); PG8_BAR; PG8_SCHED;
	s_add_i32 s78, s81, s22
	v_lshl_add_u64 v[218:219], v[218:219], 0, s[18:19]
	s_mov_b32 m0, s78
	ds_read_b128 v[186:189], v228 offset:49152
	ds_read_b128 v[190:193], v228 offset:50176
	ds_read_b128 v[194:197], v228 offset:51200
	ds_read_b128 v[198:201], v228 offset:52224
	ds_read_b128 v[202:205], v228 offset:53248
	ds_read_b128 v[206:209], v228 offset:54272
	ds_read_b128 v[210:213], v228 offset:55296
	ds_read_b128 v[214:217], v228 offset:56320
	global_load_lds_dwordx4 v[218:219], off
	s_add_i32 m0, s78, 0x2000
	s_add_u32 s8, s8, 0x40080
	v_lshl_add_u64 v[218:219], v[220:221], 0, s[18:19]
	s_addc_u32 s9, s9, 0
	s_add_i32 s78, s82, s22
	global_load_lds_dwordx4 v[218:219], off
	v_lshl_add_u64 v[218:219], s[8:9], 0, v[136:137]
	s_mov_b32 m0, s78
	s_nop 0
	global_load_lds_dwordx4 v[218:219], off
	v_lshl_add_u64 v[244:245], s[8:9], 0, v[132:133]
	v_lshl_add_u64 v[246:247], v[222:223], 0, s[18:19]
	v_lshl_add_u64 v[218:219], v[230:231], 0, s[18:19]
	s_waitcnt vmcnt(5)
	s_waitcnt lgkmcnt(0)
	s_barrier
	s_setprio 1
	s_waitcnt lgkmcnt(0)
	v_mfma_f32_16x16x32_bf16 v[60:63], v[128:131], v[186:189], v[60:63]
	v_mfma_f32_16x16x32_bf16 v[56:59], v[162:165], v[186:189], v[56:59]
	v_mfma_f32_16x16x32_bf16 v[44:47], v[128:131], v[194:197], v[44:47]
	v_mfma_f32_16x16x32_bf16 v[40:43], v[162:165], v[194:197], v[40:43]
	s_add_i32 m0, s78, 0x2000
	v_mfma_f32_16x16x32_bf16 v[28:31], v[128:131], v[202:205], v[28:31]
	global_load_lds_dwordx4 v[244:245], off
	v_mfma_f32_16x16x32_bf16 v[24:27], v[162:165], v[202:205], v[24:27]
	v_mfma_f32_16x16x32_bf16 v[12:15], v[128:131], v[210:213], v[12:15]
	v_mfma_f32_16x16x32_bf16 v[8:11], v[162:165], v[210:213], v[8:11]
	v_mfma_f32_16x16x32_bf16 v[60:63], v[158:161], v[190:193], v[60:63]
	v_mfma_f32_16x16x32_bf16 v[56:59], v[166:169], v[190:193], v[56:59]
	v_mfma_f32_16x16x32_bf16 v[44:47], v[158:161], v[198:201], v[44:47]
	v_mfma_f32_16x16x32_bf16 v[40:43], v[166:169], v[198:201], v[40:43]
	s_mov_b32 m0, s61
	v_mfma_f32_16x16x32_bf16 v[28:31], v[158:161], v[206:209], v[28:31]
	global_load_lds_dwordx4 v[246:247], off
	v_mfma_f32_16x16x32_bf16 v[24:27], v[166:169], v[206:209], v[24:27]
	v_mfma_f32_16x16x32_bf16 v[12:15], v[158:161], v[214:217], v[12:15]
	v_mfma_f32_16x16x32_bf16 v[8:11], v[166:169], v[214:217], v[8:11]
	s_setprio 0
	s_setprio 1
	v_mfma_f32_16x16x32_bf16 v[52:55], v[170:173], v[186:189], v[52:55]
	v_mfma_f32_16x16x32_bf16 v[48:51], v[178:181], v[186:189], v[48:51]
	v_mfma_f32_16x16x32_bf16 v[36:39], v[170:173], v[194:197], v[36:39]
	v_mfma_f32_16x16x32_bf16 v[32:35], v[178:181], v[194:197], v[32:35]
	s_mov_b32 m0, s69
	v_mfma_f32_16x16x32_bf16 v[20:23], v[170:173], v[202:205], v[20:23]
	global_load_lds_dwordx4 v[218:219], off
	v_mfma_f32_16x16x32_bf16 v[16:19], v[178:181], v[202:205], v[16:19]
	v_mfma_f32_16x16x32_bf16 v[4:7], v[170:173], v[210:213], v[4:7]
	v_mfma_f32_16x16x32_bf16 v[0:3], v[178:181], v[210:213], v[0:3]
	v_mfma_f32_16x16x32_bf16 v[52:55], v[174:177], v[190:193], v[52:55]
	v_mfma_f32_16x16x32_bf16 v[48:51], v[182:185], v[190:193], v[48:51]
	v_mfma_f32_16x16x32_bf16 v[36:39], v[174:177], v[198:201], v[36:39]
	v_mfma_f32_16x16x32_bf16 v[32:35], v[182:185], v[198:201], v[32:35]
	v_mfma_f32_16x16x32_bf16 v[20:23], v[174:177], v[206:209], v[20:23]
	v_mfma_f32_16x16x32_bf16 v[16:19], v[182:185], v[206:209], v[16:19]
	v_mfma_f32_16x16x32_bf16 v[4:7], v[174:177], v[214:217], v[4:7]
	v_mfma_f32_16x16x32_bf16 v[0:3], v[182:185], v[214:217], v[0:3]
	s_setprio 0
	s_barrier
	s_add_i32 s80, s80, 2
	s_add_u32 s6, s6, 0x100
	s_addc_u32 s7, s7, 0
	s_add_u32 s71, s71, 0x100
	s_addc_u32 s73, s73, 0
	s_cmp_gt_u32 s80, 13
	s_cbranch_scc0 .LBB0_835
	s_and_b64 vcc, exec, s[20:21]
	s_cbranch_vccz .LBB0_838
	s_barrier

; #define PG8_STAGE(bufoff, gbase, voff) do { _Pragma("unroll") for (int _i = 0; _i < 2; ++_i) \
;         __builtin_amdgcn_global_load_lds((const unsigned*)((const char*)(gbase) + (voff)[_i]), (PG8_LAS unsigned*)(lds + (bufoff) + ldsw + _i * 8192), 16, 0, 0); } while (0)
; #define PG8_LDA(dst, b, h) do { _Pragma("unroll") for (int m = 0; m < 4; ++m) _Pragma("unroll") for (int k = 0; k < 2; ++k) dst[m][k] = *(const PG8_LAS bf16x8*)(lds + PG8_SA(b, h) + aoff + m * 2048 + k * 1024); } while (0)
; #define PG8_LDB(dst, b, h) do { _Pragma("unroll") for (int n = 0; n < 2; ++n) _Pragma("unroll") for (int k = 0; k < 2; ++k) dst[n][k] = *(const PG8_LAS bf16x8*)(lds + PG8_SB(b, h) + boff + n * 2048 + k * 1024); } while (0)
; #define PG8_MMA(ai, bj, At, Bt) do { __builtin_amdgcn_s_setprio(1); _Pragma("unroll") for (int m = 0; m < 4; ++m) _Pragma("unroll") for (int n = 0; n < 2; ++n) _Pragma("unroll") for (int k = 0; k < 2; ++k) \
;         acc[ai][bj][m][n] = __builtin_amdgcn_mfma_f32_16x16x32_bf16(Bt[n][k], At[m][k], acc[ai][bj][m][n], 0, 0, 0); __builtin_amdgcn_s_setprio(0); } while (0)
; #define PG8_WAIT_V(n) asm volatile("s_waitcnt vmcnt(" #n ")" ::: "memory")
; #define PG8_WAIT_L(n) asm volatile("s_waitcnt lgkmcnt(" #n ")" ::: "memory")
; #define PG8_BAR __builtin_amdgcn_s_barrier()
; #define PG8_SCHED __builtin_amdgcn_sched_barrier(0)
; template <class Epi, class Sched, bool ALIGN_EPI = false, bool SP2 = false>
; __device__ __forceinline__ void gemm_phase(PG8_LAS unsigned char* lds, const Gemm g, const Sched& S, const Epi& E) {
;     ...
;             PG8_LDB(B0, 0, 0); PG8_LDB(B1, 0, 1); PG8_SCHED; PG8_LDA(At, 0, 0); PG8_STAGE(PG8_SA(1, 1), a1 + hstep, voffA);
;             PG8_WAIT_V(8); PG8_WAIT_L(0); PG8_BAR; PG8_MMA(0, 0, At, B0); PG8_MMA(0, 1, At, B1); PG8_BAR; PG8_SCHED;
;             PG8_LDA(At, 0, 1); PG8_STAGE(PG8_SB(0, 0), b2, voffB); PG8_STAGE(PG8_SB(0, 1), b2 + hstep, voffB); PG8_STAGE(PG8_SA(0, 0), a2, voffA);
.LBB0_993:
	ds_read_b128 v[152:155], v149
	ds_read_b128 v[156:159], v149 offset:1024
	ds_read_b128 v[160:163], v149 offset:2048
	ds_read_b128 v[164:167], v149 offset:3072
	ds_read_b128 v[168:171], v150
	ds_read_b128 v[172:175], v150 offset:1024
	ds_read_b128 v[176:179], v150 offset:2048
	ds_read_b128 v[180:183], v150 offset:3072
	s_add_u32 s38, s36, 0xfffc0080
	s_addc_u32 s39, s37, -1
	s_cmp_eq_u32 s57, 12
	s_cselect_b32 s41, s21, s39
	s_cselect_b32 s40, s51, s38
	s_cselect_b32 s39, s19, s56
	s_cselect_b32 s38, s52, s53
	v_lshl_add_u64 v[144:145], s[36:37], 0, v[136:137]
	s_add_i32 m0, s25, 0xc000
	ds_read_b128 v[184:187], v151
	ds_read_b128 v[188:191], v151 offset:1024
	ds_read_b128 v[192:195], v151 offset:2048
	ds_read_b128 v[196:199], v151 offset:3072
	ds_read_b128 v[200:203], v151 offset:4096
	ds_read_b128 v[204:207], v151 offset:5120
	ds_read_b128 v[208:211], v151 offset:6144
	ds_read_b128 v[212:215], v151 offset:7168
	global_load_lds_dwordx4 v[144:145], off
	v_lshl_add_u64 v[144:145], s[36:37], 0, v[138:139]
	s_add_i32 m0, s25, 0xe000
	s_nop 0
	global_load_lds_dwordx4 v[144:145], off
	s_waitcnt vmcnt(8)
	s_waitcnt lgkmcnt(0)
	s_barrier
	s_setprio 1
	s_waitcnt lgkmcnt(0)
	v_mfma_f32_16x16x32_bf16 v[124:127], v[152:155], v[184:187], v[124:127]
	v_mfma_f32_16x16x32_bf16 v[120:123], v[160:163], v[184:187], v[120:123]
	v_mfma_f32_16x16x32_bf16 v[116:119], v[152:155], v[192:195], v[116:119]
	v_mfma_f32_16x16x32_bf16 v[108:111], v[160:163], v[192:195], v[108:111]
	v_mfma_f32_16x16x32_bf16 v[100:103], v[152:155], v[200:203], v[100:103]
	v_mfma_f32_16x16x32_bf16 v[92:95], v[160:163], v[200:203], v[92:95]
	v_mfma_f32_16x16x32_bf16 v[84:87], v[152:155], v[208:211], v[84:87]
	v_mfma_f32_16x16x32_bf16 v[76:79], v[160:163], v[208:211], v[76:79]
	v_mfma_f32_16x16x32_bf16 v[124:127], v[156:159], v[188:191], v[124:127]
	v_mfma_f32_16x16x32_bf16 v[120:123], v[164:167], v[188:191], v[120:123]
	v_mfma_f32_16x16x32_bf16 v[116:119], v[156:159], v[196:199], v[116:119]
	v_mfma_f32_16x16x32_bf16 v[108:111], v[164:167], v[196:199], v[108:111]
	v_mfma_f32_16x16x32_bf16 v[100:103], v[156:159], v[204:207], v[100:103]
	v_mfma_f32_16x16x32_bf16 v[92:95], v[164:167], v[204:207], v[92:95]
	v_mfma_f32_16x16x32_bf16 v[84:87], v[156:159], v[212:215], v[84:87]
	v_mfma_f32_16x16x32_bf16 v[76:79], v[164:167], v[212:215], v[76:79]
	s_setprio 0
	s_setprio 1
	v_mfma_f32_16x16x32_bf16 v[112:115], v[168:171], v[184:187], v[112:115]
	v_mfma_f32_16x16x32_bf16 v[104:107], v[176:179], v[184:187], v[104:107]
	v_mfma_f32_16x16x32_bf16 v[96:99], v[168:171], v[192:195], v[96:99]
	v_mfma_f32_16x16x32_bf16 v[88:91], v[176:179], v[192:195], v[88:91]
	v_mfma_f32_16x16x32_bf16 v[80:83], v[168:171], v[200:203], v[80:83]
	v_mfma_f32_16x16x32_bf16 v[72:75], v[176:179], v[200:203], v[72:75]
	v_mfma_f32_16x16x32_bf16 v[68:71], v[168:171], v[208:211], v[68:71]
	v_mfma_f32_16x16x32_bf16 v[64:67], v[176:179], v[208:211], v[64:67]
	v_mfma_f32_16x16x32_bf16 v[112:115], v[172:175], v[188:191], v[112:115]
	v_mfma_f32_16x16x32_bf16 v[104:107], v[180:183], v[188:191], v[104:107]
	v_mfma_f32_16x16x32_bf16 v[96:99], v[172:175], v[196:199], v[96:99]
	v_mfma_f32_16x16x32_bf16 v[88:91], v[180:183], v[196:199], v[88:91]
	v_mfma_f32_16x16x32_bf16 v[80:83], v[172:175], v[204:207], v[80:83]
	v_mfma_f32_16x16x32_bf16 v[72:75], v[180:183], v[204:207], v[72:75]
	v_mfma_f32_16x16x32_bf16 v[68:71], v[172:175], v[212:215], v[68:71]
	v_mfma_f32_16x16x32_bf16 v[64:67], v[180:183], v[212:215], v[64:67]
	s_setprio 0
	s_barrier
	s_add_i32 s58, s46, s2
	v_lshl_add_u64 v[144:145], s[38:39], 0, v[132:133]
	s_mov_b32 m0, s58
	ds_read_b128 v[184:187], v151 offset:16384
	ds_read_b128 v[188:191], v151 offset:17408
	ds_read_b128 v[192:195], v151 offset:18432
	ds_read_b128 v[196:199], v151 offset:19456
	ds_read_b128 v[200:203], v151 offset:20480
	ds_read_b128 v[204:207], v151 offset:21504
	ds_read_b128 v[208:211], v151 offset:22528
	ds_read_b128 v[212:215], v151 offset:23552
	global_load_lds_dwordx4 v[144:145], off
	s_add_i32 m0, s58, 0x2000
	s_add_u32 s58, s38, 0x40000
	v_lshl_add_u64 v[216:217], s[38:39], 0, v[128:129]
	s_addc_u32 s59, s39, 0
	s_add_i32 s60, s47, s2
	global_load_lds_dwordx4 v[216:217], off
	v_lshl_add_u64 v[218:219], s[58:59], 0, v[132:133]
	s_mov_b32 m0, s60
	v_lshl_add_u64 v[220:221], s[40:41], 0, v[130:131]
	global_load_lds_dwordx4 v[218:219], off
	v_lshl_add_u64 v[244:245], s[58:59], 0, v[128:129]
	v_lshl_add_u64 v[218:219], s[40:41], 0, v[134:135]
	s_waitcnt vmcnt(5)
	s_waitcnt lgkmcnt(0)
	s_barrier
; #define PG8_STAGE(bufoff, gbase, voff) do { _Pragma("unroll") for (int _i = 0; _i < 2; ++_i) \
;         __builtin_amdgcn_global_load_lds((const unsigned*)((const char*)(gbase) + (voff)[_i]), (PG8_LAS unsigned*)(lds + (bufoff) + ldsw + _i * 8192), 16, 0, 0); } while (0)
; #define PG8_LDA(dst, b, h) do { _Pragma("unroll") for (int m = 0; m < 4; ++m) _Pragma("unroll") for (int k = 0; k < 2; ++k) dst[m][k] = *(const PG8_LAS bf16x8*)(lds + PG8_SA(b, h) + aoff + m * 2048 + k * 1024); } while (0)
; #define PG8_LDB(dst, b, h) do { _Pragma("unroll") for (int n = 0; n < 2; ++n) _Pragma("unroll") for (int k = 0; k < 2; ++k) dst[n][k] = *(const PG8_LAS bf16x8*)(lds + PG8_SB(b, h) + boff + n * 2048 + k * 1024); } while (0)
; #define PG8_MMA(ai, bj, At, Bt) do { __builtin_amdgcn_s_setprio(1); _Pragma("unroll") for (int m = 0; m < 4; ++m) _Pragma("unroll") for (int n = 0; n < 2; ++n) _Pragma("unroll") for (int k = 0; k < 2; ++k) \
;         acc[ai][bj][m][n] = __builtin_amdgcn_mfma_f32_16x16x32_bf16(Bt[n][k], At[m][k], acc[ai][bj][m][n], 0, 0, 0); __builtin_amdgcn_s_setprio(0); } while (0)
; #define PG8_WAIT_V(n) asm volatile("s_waitcnt vmcnt(" #n ")" ::: "memory")
; #define PG8_WAIT_L(n) asm volatile("s_waitcnt lgkmcnt(" #n ")" ::: "memory")
; #define PG8_BAR __builtin_amdgcn_s_barrier()
; #define PG8_SCHED __builtin_amdgcn_sched_barrier(0)
; template <class Epi, class Sched, bool ALIGN_EPI = false, bool SP2 = false>
; __device__ __forceinline__ void gemm_phase(PG8_LAS unsigned char* lds, const Gemm g, const Sched& S, const Epi& E) {
;     ...
;             PG8_WAIT_V(8); PG8_WAIT_L(0); PG8_BAR; PG8_MMA(1, 0, At, B0); PG8_MMA(1, 1, At, B1); PG8_BAR; PG8_SCHED;
;             PG8_LDB(B0, 1, 0); PG8_LDB(B1, 1, 1); PG8_SCHED; PG8_LDA(At, 1, 0); PG8_STAGE(PG8_SA(0, 1), a2 + hstep, voffA);
;             PG8_WAIT_V(8); PG8_WAIT_L(0); PG8_BAR; PG8_MMA(0, 0, At, B0); PG8_MMA(0, 1, At, B1); PG8_BAR; PG8_SCHED;
	s_setprio 1
	s_waitcnt lgkmcnt(0)
	v_mfma_f32_16x16x32_bf16 v[60:63], v[152:155], v[184:187], v[60:63]
	v_mfma_f32_16x16x32_bf16 v[56:59], v[160:163], v[184:187], v[56:59]
	v_mfma_f32_16x16x32_bf16 v[52:55], v[152:155], v[192:195], v[52:55]
	v_mfma_f32_16x16x32_bf16 v[44:47], v[160:163], v[192:195], v[44:47]
	s_add_i32 m0, s60, 0x2000
	v_mfma_f32_16x16x32_bf16 v[36:39], v[152:155], v[200:203], v[36:39]
	global_load_lds_dwordx4 v[244:245], off
	v_mfma_f32_16x16x32_bf16 v[28:31], v[160:163], v[200:203], v[28:31]
	v_mfma_f32_16x16x32_bf16 v[20:23], v[152:155], v[208:211], v[20:23]
	v_mfma_f32_16x16x32_bf16 v[12:15], v[160:163], v[208:211], v[12:15]
	v_mfma_f32_16x16x32_bf16 v[60:63], v[156:159], v[188:191], v[60:63]
	v_mfma_f32_16x16x32_bf16 v[56:59], v[164:167], v[188:191], v[56:59]
	v_mfma_f32_16x16x32_bf16 v[52:55], v[156:159], v[196:199], v[52:55]
	v_mfma_f32_16x16x32_bf16 v[44:47], v[164:167], v[196:199], v[44:47]
	s_mov_b32 m0, s25
	v_mfma_f32_16x16x32_bf16 v[36:39], v[156:159], v[204:207], v[36:39]
	global_load_lds_dwordx4 v[218:219], off
	v_mfma_f32_16x16x32_bf16 v[28:31], v[164:167], v[204:207], v[28:31]
	v_mfma_f32_16x16x32_bf16 v[20:23], v[156:159], v[212:215], v[20:23]
	v_mfma_f32_16x16x32_bf16 v[12:15], v[164:167], v[212:215], v[12:15]
	s_setprio 0
	s_setprio 1
	v_mfma_f32_16x16x32_bf16 v[48:51], v[168:171], v[184:187], v[48:51]
	v_mfma_f32_16x16x32_bf16 v[40:43], v[176:179], v[184:187], v[40:43]
	v_mfma_f32_16x16x32_bf16 v[32:35], v[168:171], v[192:195], v[32:35]
	v_mfma_f32_16x16x32_bf16 v[24:27], v[176:179], v[192:195], v[24:27]
	s_mov_b32 m0, s33
	v_mfma_f32_16x16x32_bf16 v[16:19], v[168:171], v[200:203], v[16:19]
	global_load_lds_dwordx4 v[220:221], off
	v_mfma_f32_16x16x32_bf16 v[8:11], v[176:179], v[200:203], v[8:11]
	v_mfma_f32_16x16x32_bf16 v[4:7], v[168:171], v[208:211], v[4:7]
	v_mfma_f32_16x16x32_bf16 v[0:3], v[176:179], v[208:211], v[0:3]
	v_mfma_f32_16x16x32_bf16 v[48:51], v[172:175], v[188:191], v[48:51]
	v_mfma_f32_16x16x32_bf16 v[40:43], v[180:183], v[188:191], v[40:43]
	v_mfma_f32_16x16x32_bf16 v[32:35], v[172:175], v[196:199], v[32:35]
	v_mfma_f32_16x16x32_bf16 v[24:27], v[180:183], v[196:199], v[24:27]
	v_mfma_f32_16x16x32_bf16 v[16:19], v[172:175], v[204:207], v[16:19]
	v_mfma_f32_16x16x32_bf16 v[8:11], v[180:183], v[204:207], v[8:11]
	v_mfma_f32_16x16x32_bf16 v[4:7], v[172:175], v[212:215], v[4:7]
	v_mfma_f32_16x16x32_bf16 v[0:3], v[180:183], v[212:215], v[0:3]
	s_setprio 0
	s_barrier
	s_add_i32 s58, 0, 0x18000
	s_add_i32 s59, 0, 0x1c000
	v_add_u32_e32 v164, s58, v147
	v_add_u32_e32 v180, s59, v147
	ds_read_b128 v[152:155], v164
	ds_read_b128 v[156:159], v164 offset:1024
	ds_read_b128 v[160:163], v164 offset:2048
	ds_read_b128 v[164:167], v164 offset:3072
	ds_read_b128 v[168:171], v180
	ds_read_b128 v[172:175], v180 offset:1024
	ds_read_b128 v[176:179], v180 offset:2048
	ds_read_b128 v[180:183], v180 offset:3072
	s_add_u32 s40, s40, 0x40000
	s_addc_u32 s41, s41, 0
	s_mov_b32 m0, s35
	v_lshl_add_u64 v[222:223], s[40:41], 0, v[134:135]
	ds_read_b128 v[184:187], v151 offset:32768
	ds_read_b128 v[188:191], v151 offset:33792
	ds_read_b128 v[192:195], v151 offset:34816
	ds_read_b128 v[196:199], v151 offset:35840
	ds_read_b128 v[200:203], v151 offset:36864
	ds_read_b128 v[204:207], v151 offset:37888
	ds_read_b128 v[208:211], v151 offset:38912
	ds_read_b128 v[212:215], v151 offset:39936
	global_load_lds_dwordx4 v[222:223], off
	v_lshl_add_u64 v[222:223], s[40:41], 0, v[130:131]
	s_mov_b32 m0, s42
	s_nop 0
	global_load_lds_dwordx4 v[222:223], off
	s_waitcnt vmcnt(8)
	s_waitcnt lgkmcnt(0)
	s_barrier
	s_setprio 1
	s_waitcnt lgkmcnt(0)
	v_mfma_f32_16x16x32_bf16 v[124:127], v[152:155], v[184:187], v[124:127]
	v_mfma_f32_16x16x32_bf16 v[120:123], v[160:163], v[184:187], v[120:123]
	v_mfma_f32_16x16x32_bf16 v[116:119], v[152:155], v[192:195], v[116:119]
	v_mfma_f32_16x16x32_bf16 v[108:111], v[160:163], v[192:195], v[108:111]
	v_mfma_f32_16x16x32_bf16 v[100:103], v[152:155], v[200:203], v[100:103]
	v_mfma_f32_16x16x32_bf16 v[92:95], v[160:163], v[200:203], v[92:95]
	v_mfma_f32_16x16x32_bf16 v[84:87], v[152:155], v[208:211], v[84:87]
	v_mfma_f32_16x16x32_bf16 v[76:79], v[160:163], v[208:211], v[76:79]
	v_mfma_f32_16x16x32_bf16 v[124:127], v[156:159], v[188:191], v[124:127]
	v_mfma_f32_16x16x32_bf16 v[120:123], v[164:167], v[188:191], v[120:123]
	v_mfma_f32_16x16x32_bf16 v[116:119], v[156:159], v[196:199], v[116:119]
	v_mfma_f32_16x16x32_bf16 v[108:111], v[164:167], v[196:199], v[108:111]
	v_mfma_f32_16x16x32_bf16 v[100:103], v[156:159], v[204:207], v[100:103]
	v_mfma_f32_16x16x32_bf16 v[92:95], v[164:167], v[204:207], v[92:95]
	v_mfma_f32_16x16x32_bf16 v[84:87], v[156:159], v[212:215], v[84:87]
	v_mfma_f32_16x16x32_bf16 v[76:79], v[164:167], v[212:215], v[76:79]
	s_setprio 0
	s_setprio 1
	v_mfma_f32_16x16x32_bf16 v[112:115], v[168:171], v[184:187], v[112:115]
	v_mfma_f32_16x16x32_bf16 v[104:107], v[176:179], v[184:187], v[104:107]
	v_mfma_f32_16x16x32_bf16 v[96:99], v[168:171], v[192:195], v[96:99]
	v_mfma_f32_16x16x32_bf16 v[88:91], v[176:179], v[192:195], v[88:91]
	v_mfma_f32_16x16x32_bf16 v[80:83], v[168:171], v[200:203], v[80:83]
	v_mfma_f32_16x16x32_bf16 v[72:75], v[176:179], v[200:203], v[72:75]
	v_mfma_f32_16x16x32_bf16 v[68:71], v[168:171], v[208:211], v[68:71]
	v_mfma_f32_16x16x32_bf16 v[64:67], v[176:179], v[208:211], v[64:67]
	v_mfma_f32_16x16x32_bf16 v[112:115], v[172:175], v[188:191], v[112:115]
	v_mfma_f32_16x16x32_bf16 v[104:107], v[180:183], v[188:191], v[104:107]
	v_mfma_f32_16x16x32_bf16 v[96:99], v[172:175], v[196:199], v[96:99]
	v_mfma_f32_16x16x32_bf16 v[88:91], v[180:183], v[196:199], v[88:91]
	v_mfma_f32_16x16x32_bf16 v[80:83], v[172:175], v[204:207], v[80:83]
	v_mfma_f32_16x16x32_bf16 v[72:75], v[180:183], v[204:207], v[72:75]
	v_mfma_f32_16x16x32_bf16 v[68:71], v[172:175], v[212:215], v[68:71]
	v_mfma_f32_16x16x32_bf16 v[64:67], v[180:183], v[212:215], v[64:67]
	s_setprio 0
	s_barrier
; #define PG8_STAGE(bufoff, gbase, voff) do { _Pragma("unroll") for (int _i = 0; _i < 2; ++_i) \
;         __builtin_amdgcn_global_load_lds((const unsigned*)((const char*)(gbase) + (voff)[_i]), (PG8_LAS unsigned*)(lds + (bufoff) + ldsw + _i * 8192), 16, 0, 0); } while (0)
; #define PG8_LDA(dst, b, h) do { _Pragma("unroll") for (int m = 0; m < 4; ++m) _Pragma("unroll") for (int k = 0; k < 2; ++k) dst[m][k] = *(const PG8_LAS bf16x8*)(lds + PG8_SA(b, h) + aoff + m * 2048 + k * 1024); } while (0)
; #define PG8_MMA(ai, bj, At, Bt) do { __builtin_amdgcn_s_setprio(1); _Pragma("unroll") for (int m = 0; m < 4; ++m) _Pragma("unroll") for (int n = 0; n < 2; ++n) _Pragma("unroll") for (int k = 0; k < 2; ++k) \
;         acc[ai][bj][m][n] = __builtin_amdgcn_mfma_f32_16x16x32_bf16(Bt[n][k], At[m][k], acc[ai][bj][m][n], 0, 0, 0); __builtin_amdgcn_s_setprio(0); } while (0)
; #define PG8_WAIT_V(n) asm volatile("s_waitcnt vmcnt(" #n ")" ::: "memory")
; #define PG8_WAIT_L(n) asm volatile("s_waitcnt lgkmcnt(" #n ")" ::: "memory")
; #define PG8_BAR __builtin_amdgcn_s_barrier()
; #define PG8_SCHED __builtin_amdgcn_sched_barrier(0)
; template <class Epi, class Sched, bool ALIGN_EPI = false, bool SP2 = false>
; __device__ __forceinline__ void gemm_phase(PG8_LAS unsigned char* lds, const Gemm g, const Sched& S, const Epi& E) {
;     ...
;         for (int t = 0; t < nt; t += 2) {
;             const bool last = (t == nt - 2);
;             const char* a1 = cA + (size_t)(t + 1) * kstep;
;             const char* a2 = last ? nA : cA + (size_t)(t + 2) * kstep; const char* b2 = last ? nB : cB + (size_t)(t + 2) * kstep;
;             const char* a3 = a2 + kstep; const char* b3 = b2 + kstep;
;     ...
;             PG8_LDA(At, 1, 1); PG8_STAGE(PG8_SB(1, 0), b3, voffB); PG8_STAGE(PG8_SB(1, 1), b3 + hstep, voffB); PG8_STAGE(PG8_SA(1, 0), a3, voffA);
;             PG8_WAIT_V(8); PG8_WAIT_L(0); PG8_BAR; PG8_MMA(1, 0, At, B0); PG8_MMA(1, 1, At, B1); PG8_BAR; PG8_SCHED;
	s_add_i32 s40, s58, s2
	v_lshl_add_u64 v[144:145], v[144:145], 0, s[6:7]
	s_mov_b32 m0, s40
	ds_read_b128 v[184:187], v151 offset:49152
	ds_read_b128 v[188:191], v151 offset:50176
	ds_read_b128 v[192:195], v151 offset:51200
	ds_read_b128 v[196:199], v151 offset:52224
	ds_read_b128 v[200:203], v151 offset:53248
	ds_read_b128 v[204:207], v151 offset:54272
	ds_read_b128 v[208:211], v151 offset:55296
	ds_read_b128 v[212:215], v151 offset:56320
	global_load_lds_dwordx4 v[144:145], off
	s_add_i32 m0, s40, 0x2000
	s_add_u32 s38, s38, 0x40080
	v_lshl_add_u64 v[144:145], v[216:217], 0, s[6:7]
	s_addc_u32 s39, s39, 0
	s_add_i32 s40, s59, s2
	global_load_lds_dwordx4 v[144:145], off
	v_lshl_add_u64 v[144:145], s[38:39], 0, v[132:133]
	s_mov_b32 m0, s40
	s_nop 0
	global_load_lds_dwordx4 v[144:145], off
	v_lshl_add_u64 v[244:245], s[38:39], 0, v[128:129]
	v_lshl_add_u64 v[246:247], v[218:219], 0, s[6:7]
	v_lshl_add_u64 v[144:145], v[220:221], 0, s[6:7]
	s_waitcnt vmcnt(5)
	s_waitcnt lgkmcnt(0)
	s_barrier
	s_setprio 1
	s_waitcnt lgkmcnt(0)
	v_mfma_f32_16x16x32_bf16 v[60:63], v[152:155], v[184:187], v[60:63]
	v_mfma_f32_16x16x32_bf16 v[56:59], v[160:163], v[184:187], v[56:59]
	v_mfma_f32_16x16x32_bf16 v[52:55], v[152:155], v[192:195], v[52:55]
	v_mfma_f32_16x16x32_bf16 v[44:47], v[160:163], v[192:195], v[44:47]
	s_add_i32 m0, s40, 0x2000
	v_mfma_f32_16x16x32_bf16 v[36:39], v[152:155], v[200:203], v[36:39]
	global_load_lds_dwordx4 v[244:245], off
	v_mfma_f32_16x16x32_bf16 v[28:31], v[160:163], v[200:203], v[28:31]
	v_mfma_f32_16x16x32_bf16 v[20:23], v[152:155], v[208:211], v[20:23]
	v_mfma_f32_16x16x32_bf16 v[12:15], v[160:163], v[208:211], v[12:15]
	v_mfma_f32_16x16x32_bf16 v[60:63], v[156:159], v[188:191], v[60:63]
	v_mfma_f32_16x16x32_bf16 v[56:59], v[164:167], v[188:191], v[56:59]
	v_mfma_f32_16x16x32_bf16 v[52:55], v[156:159], v[196:199], v[52:55]
	v_mfma_f32_16x16x32_bf16 v[44:47], v[164:167], v[196:199], v[44:47]
	s_mov_b32 m0, s44
	v_mfma_f32_16x16x32_bf16 v[36:39], v[156:159], v[204:207], v[36:39]
	global_load_lds_dwordx4 v[246:247], off
	v_mfma_f32_16x16x32_bf16 v[28:31], v[164:167], v[204:207], v[28:31]
	v_mfma_f32_16x16x32_bf16 v[20:23], v[156:159], v[212:215], v[20:23]
	v_mfma_f32_16x16x32_bf16 v[12:15], v[164:167], v[212:215], v[12:15]
	s_setprio 0
	s_setprio 1
	v_mfma_f32_16x16x32_bf16 v[48:51], v[168:171], v[184:187], v[48:51]
	v_mfma_f32_16x16x32_bf16 v[40:43], v[176:179], v[184:187], v[40:43]
	v_mfma_f32_16x16x32_bf16 v[32:35], v[168:171], v[192:195], v[32:35]
	v_mfma_f32_16x16x32_bf16 v[24:27], v[176:179], v[192:195], v[24:27]
	s_mov_b32 m0, s45
	v_mfma_f32_16x16x32_bf16 v[16:19], v[168:171], v[200:203], v[16:19]
	global_load_lds_dwordx4 v[144:145], off
	v_mfma_f32_16x16x32_bf16 v[8:11], v[176:179], v[200:203], v[8:11]
	v_mfma_f32_16x16x32_bf16 v[4:7], v[168:171], v[208:211], v[4:7]
	v_mfma_f32_16x16x32_bf16 v[0:3], v[176:179], v[208:211], v[0:3]
	v_mfma_f32_16x16x32_bf16 v[48:51], v[172:175], v[188:191], v[48:51]
	v_mfma_f32_16x16x32_bf16 v[40:43], v[180:183], v[188:191], v[40:43]
	v_mfma_f32_16x16x32_bf16 v[32:35], v[172:175], v[196:199], v[32:35]
	v_mfma_f32_16x16x32_bf16 v[24:27], v[180:183], v[196:199], v[24:27]
	v_mfma_f32_16x16x32_bf16 v[16:19], v[172:175], v[204:207], v[16:19]
	v_mfma_f32_16x16x32_bf16 v[8:11], v[180:183], v[204:207], v[8:11]
	v_mfma_f32_16x16x32_bf16 v[4:7], v[172:175], v[212:215], v[4:7]
	v_mfma_f32_16x16x32_bf16 v[0:3], v[180:183], v[212:215], v[0:3]
	s_setprio 0
	s_barrier
	s_add_i32 s57, s57, 2
	s_add_u32 s36, s36, 0x100
	s_addc_u32 s37, s37, 0
	s_add_u32 s53, s53, 0x100
	s_addc_u32 s56, s56, 0
	s_cmp_gt_u32 s57, 13
	s_cbranch_scc0 .LBB0_993
	s_and_b64 vcc, exec, s[8:9]
	s_cbranch_vccz .LBB0_996
	s_barrier
